# gate-merge gate epilogue: branch tiles prefetched 3 row-groups ahead with counted vmcnt; fin phase invariant vectors hoisted
# speedup vs baseline: 1.0185x; 1.0185x over previous
; __device__ __forceinline__ void phase_fin(const Params& p, int l, int Mrows, char* smem) {
;     ...
;   uint2 gf[4], gb[4], gz[4], yf[4], yb[4], yu[4];
;   auto load_item = [&](int it) {
;     const int r0 = it * 32;
; #pragma unroll
;     for (int k = 0; k < 4; ++k) {
;       const size_t row = (size_t)(r0 + wid + k * NW);
;       gf[k] = *reinterpret_cast<const uint2*>(OGF + row * 256 + lane * 4);
;       gb[k] = *reinterpret_cast<const uint2*>(OGB + row * 256 + lane * 4);
;       gz[k] = *reinterpret_cast<const uint2*>(PB + row * PBW + PB_Z + lane * 4);
;       const int e = tid + k * NT, rr = e >> 6, c4 = (e & 63) * 4;
;       const size_t row2 = (size_t)(r0 + rr);
;       yf[k] = *reinterpret_cast<const uint2*>(O5F + row2 * 256 + c4);
;       yb[k] = *reinterpret_cast<const uint2*>(O5B + row2 * 256 + c4);
;       yu[k] = *reinterpret_cast<const uint2*>(PB + row2 * PBW + c4);
;     }
;   };
;   if ((int)blockIdx.x < items) load_item(blockIdx.x);
.LBB0_1340:
	s_or_b64 exec, exec, s[0:1]
	s_cmp_eq_u32 s88, 3
	s_mov_b32 s0, 0x10000
	s_cselect_b32 s26, s0, 0x12000
	s_lshr_b32 s4, s26, 5
	s_cmp_lt_i32 s68, s4
	s_cbranch_scc0 .LBB0_1345
	v_ashrrev_i32_e32 v20, 6, v2
	v_readlane_b32 s5, v254, 12
	v_readlane_b32 s30, v254, 6
	v_lshlrev_b32_e32 v1, 2, v2
	v_add_u32_e32 v22, s5, v20
	v_ashrrev_i32_e32 v23, 31, v22
	v_lshlrev_b64 v[4:5], 9, v[22:23]
	v_readlane_b32 s31, v254, 7
	v_and_b32_e32 v1, 0xfc, v1
	v_readlane_b32 s34, v254, 8
	v_mov_b64_e32 v[12:13], s[84:85]
	s_movk_i32 s2, 0xe00
	v_lshl_add_u64 v[6:7], s[30:31], 0, v[4:5]
	v_lshlrev_b32_e32 v8, 1, v1
	v_mov_b32_e32 v9, v0
	v_readlane_b32 s35, v254, 9
	v_mad_i64_i32 v[14:15], s[0:1], v22, s2, v[12:13]
	v_lshl_add_u64 v[6:7], v[6:7], 0, v[8:9]
	v_lshl_add_u64 v[10:11], s[34:35], 0, v[4:5]
	v_readlane_b32 s0, v254, 10
	v_lshl_add_u64 v[10:11], v[10:11], 0, v[8:9]
	v_lshl_add_u64 v[14:15], v[14:15], 0, v[8:9]
	v_readlane_b32 s24, v254, 2
	v_readlane_b32 s28, v254, 4
	global_load_dwordx2 v[24:25], v[6:7], off
	global_load_dwordx2 v[26:27], v[10:11], off
	global_load_dwordx2 v[28:29], v[14:15], off offset:2048
	global_load_dwordx2 v[30:31], v[14:15], off
	v_add_u32_e32 v6, s0, v20
	v_readlane_b32 s25, v254, 3
	v_readlane_b32 s29, v254, 5
	v_ashrrev_i32_e32 v7, 31, v6
	v_lshl_add_u64 v[16:17], s[24:25], 0, v[4:5]
	v_lshl_add_u64 v[4:5], s[28:29], 0, v[4:5]
	v_lshlrev_b64 v[10:11], 9, v[6:7]
	v_add_u32_e32 v3, 0x200, v2
	v_lshl_add_u64 v[16:17], v[16:17], 0, v[8:9]
	v_lshl_add_u64 v[4:5], v[4:5], 0, v[8:9]
	v_lshl_add_u64 v[14:15], s[30:31], 0, v[10:11]
	v_lshl_add_u64 v[10:11], s[34:35], 0, v[10:11]
	v_ashrrev_i32_e32 v21, 6, v3
	v_lshl_add_u64 v[14:15], v[14:15], 0, v[8:9]
	v_lshl_add_u64 v[10:11], v[10:11], 0, v[8:9]
	global_load_dwordx2 v[32:33], v[16:17], off
	global_load_dwordx2 v[34:35], v[4:5], off
	global_load_dwordx2 v[36:37], v[14:15], off
	global_load_dwordx2 v[38:39], v[10:11], off
	v_mad_i64_i32 v[4:5], s[0:1], v6, s2, v[12:13]
	v_add_u32_e32 v6, s5, v21
	v_ashrrev_i32_e32 v7, 31, v6
	v_lshlrev_b64 v[10:11], 9, v[6:7]
	v_mad_i64_i32 v[6:7], s[0:1], v6, s2, v[12:13]
	v_lshl_add_u64 v[4:5], v[4:5], 0, v[8:9]
	v_lshl_add_u64 v[14:15], s[24:25], 0, v[10:11]
	v_lshl_add_u64 v[10:11], s[28:29], 0, v[10:11]
	v_readlane_b32 s0, v254, 11
	v_add_u32_e32 v3, 0x400, v2
	v_lshl_add_u64 v[14:15], v[14:15], 0, v[8:9]
	v_lshl_add_u64 v[10:11], v[10:11], 0, v[8:9]
	v_lshl_add_u64 v[6:7], v[6:7], 0, v[8:9]
	global_load_dwordx2 v[40:41], v[4:5], off offset:2048
	global_load_dwordx2 v[42:43], v[14:15], off
	global_load_dwordx2 v[44:45], v[10:11], off
	global_load_dwordx2 v[46:47], v[6:7], off
	v_add_u32_e32 v4, s0, v20
	v_ashrrev_i32_e32 v92, 6, v3
	v_ashrrev_i32_e32 v5, 31, v4
	v_add_u32_e32 v14, s5, v92
	v_lshlrev_b64 v[6:7], 9, v[4:5]
	v_ashrrev_i32_e32 v15, 31, v14
	v_lshl_add_u64 v[10:11], s[30:31], 0, v[6:7]
	v_lshl_add_u64 v[6:7], s[34:35], 0, v[6:7]
	v_lshlrev_b64 v[16:17], 9, v[14:15]
	v_lshl_add_u64 v[10:11], v[10:11], 0, v[8:9]
	v_lshl_add_u64 v[6:7], v[6:7], 0, v[8:9]
	v_mad_i64_i32 v[4:5], s[0:1], v4, s2, v[12:13]
	v_lshl_add_u64 v[18:19], s[24:25], 0, v[16:17]
	v_lshl_add_u64 v[4:5], v[4:5], 0, v[8:9]
	v_lshl_add_u64 v[18:19], v[18:19], 0, v[8:9]
	global_load_dwordx2 v[48:49], v[10:11], off
	global_load_dwordx2 v[50:51], v[6:7], off
	global_load_dwordx2 v[52:53], v[4:5], off offset:2048
	global_load_dwordx2 v[54:55], v[18:19], off
	v_mad_i64_i32 v[6:7], s[0:1], v14, s2, v[12:13]
	v_readlane_b32 s0, v254, 13
	v_lshl_add_u64 v[4:5], s[28:29], 0, v[16:17]
	v_lshl_add_u64 v[4:5], v[4:5], 0, v[8:9]
	v_add_u32_e32 v10, s0, v20
	v_ashrrev_i32_e32 v11, 31, v10
	v_lshlrev_b64 v[14:15], 9, v[10:11]
	v_lshl_add_u64 v[16:17], s[30:31], 0, v[14:15]
	v_lshl_add_u64 v[16:17], v[16:17], 0, v[8:9]
	v_lshl_add_u64 v[14:15], s[34:35], 0, v[14:15]
	v_add_u32_e32 v3, 0x600, v2
	v_lshl_add_u64 v[6:7], v[6:7], 0, v[8:9]
	v_lshl_add_u64 v[14:15], v[14:15], 0, v[8:9]
	global_load_dwordx2 v[70:71], v[4:5], off
	global_load_dwordx2 v[72:73], v[6:7], off
	global_load_dwordx2 v[74:75], v[16:17], off
	global_load_dwordx2 v[76:77], v[14:15], off
	v_ashrrev_i32_e32 v16, 6, v3
	v_add_u32_e32 v6, s5, v16
	v_ashrrev_i32_e32 v7, 31, v6
	v_mad_i64_i32 v[4:5], s[0:1], v10, s2, v[12:13]
	v_lshlrev_b64 v[10:11], 9, v[6:7]
	v_lshl_add_u64 v[4:5], v[4:5], 0, v[8:9]
	v_lshl_add_u64 v[14:15], s[24:25], 0, v[10:11]
	v_lshl_add_u64 v[10:11], s[28:29], 0, v[10:11]
	v_mad_i64_i32 v[6:7], s[0:1], v6, s2, v[12:13]
	v_lshl_add_u64 v[14:15], v[14:15], 0, v[8:9]
	v_lshl_add_u64 v[10:11], v[10:11], 0, v[8:9]
	v_lshl_add_u64 v[6:7], v[6:7], 0, v[8:9]
	global_load_dwordx2 v[84:85], v[4:5], off offset:2048
	global_load_dwordx2 v[86:87], v[14:15], off
	global_load_dwordx2 v[88:89], v[10:11], off
	global_load_dwordx2 v[90:91], v[6:7], off
	s_lshl_b32 s2, s88, 6
	v_readlane_b32 s8, v252, 18
	s_lshl_b64 s[0:1], s[2:3], 2
	v_readlane_b32 s22, v252, 32
	v_readlane_b32 s10, v252, 20
	v_readlane_b32 s11, v252, 21
	v_readlane_b32 s23, v252, 33
	s_add_u32 s0, s22, s0
	s_addc_u32 s1, s23, s1
	v_readlane_b32 s10, v255, 42
	v_lshlrev_b32_e32 v3, 4, v2
	v_readlane_b32 s9, v252, 19
	v_readlane_b32 s11, v255, 43
	s_add_u32 s6, s8, s10
	v_and_b32_e32 v4, 0xf0, v3
	v_mov_b32_e32 v5, v0
	s_addc_u32 s7, s9, s11
	v_lshl_add_u64 v[56:57], s[0:1], 0, v[4:5]
	v_lshlrev_b32_e32 v4, 2, v1
	v_and_b32_e32 v6, 15, v2
	v_lshl_add_u64 v[58:59], s[6:7], 0, v[4:5]
	v_readlane_b32 s1, v255, 9
	v_and_b32_e32 v3, 48, v2
	v_lshlrev_b32_e32 v5, 5, v20
	v_lshrrev_b32_e32 v2, 2, v2
	v_add_u32_e32 v1, s1, v3
	v_add_u32_e32 v10, 0, v3
	v_and_or_b32 v2, v2, 12, v5
	v_or_b32_e32 v3, 16, v6
	v_or_b32_e32 v7, v5, v6
; __device__ __forceinline__ float lo2f(unsigned w) { return __uint_as_float(w << 16); }
; __device__ __forceinline__ float hi2f(unsigned w) { return __uint_as_float(w & 0xffff0000u); }
; __device__ __forceinline__ float sigm(float x) { return __builtin_amdgcn_rcpf(1.f + __expf(-x)); }
; __device__ __forceinline__ void phase_fin(const Params& p, int l, int Mrows, char* smem) {
;     ...
;     f32x4 acc[2][2];
; #pragma unroll
;     for (int m = 0; m < 2; ++m)
; #pragma unroll
;       for (int n = 0; n < 2; ++n) acc[m][n] = f32x4{0.f, 0.f, 0.f, 0.f};
; #pragma unroll
;     for (int ks = 0; ks < 8; ++ks) {
;       bf16x8 a[2], g[2];
; #pragma unroll
;       for (int m = 0; m < 2; ++m) a[m] = *reinterpret_cast<const bf16x8*>(At + (m * 16 + fr) * 264 + ks * 32 + fq * 8);
; #pragma unroll
;       for (int n = 0; n < 2; ++n) g[n] = *reinterpret_cast<const bf16x8*>(Gs + (wid * 32 + n * 16 + fr) * 264 + ks * 32 + fq * 8);
; #pragma unroll
;       for (int m = 0; m < 2; ++m)
; #pragma unroll
;         for (int n = 0; n < 2; ++n) acc[m][n] = __builtin_amdgcn_mfma_f32_16x16x32_bf16(g[n], a[m], acc[m][n], 0, 0, 0);
;     }
; #pragma unroll
;     for (int m = 0; m < 2; ++m)
; #pragma unroll
;       for (int n = 0; n < 2; ++n) {
;         const int rr = m * 16 + fr, col = wid * 32 + n * 16 + fq * 4;
;         const uint2 yv = *reinterpret_cast<const uint2*>(At + rr * 264 + col);
;         const float4 b4 = *reinterpret_cast<const float4*>(glb + col);
;         uint2 w;
;         w.x = pack2(lo2f(yv.x) * sigm(acc[m][n][0] + b4.x), hi2f(yv.x) * sigm(acc[m][n][1] + b4.y));
;         w.y = pack2(lo2f(yv.y) * sigm(acc[m][n][2] + b4.z), hi2f(yv.y) * sigm(acc[m][n][3] + b4.w));
;         *reinterpret_cast<uint2*>(Y + (size_t)(r0 + rr) * 1024 + col) = w;
	v_mul_u32_u24_e32 v23, 0x210, v3
	v_lshlrev_b32_e32 v5, 1, v2
	s_movk_i32 s0, 0x210
	v_mul_u32_u24_e32 v99, 0x210, v6
	v_readlane_b32 s12, v252, 22
	v_add_u32_e32 v4, s1, v8
	v_add3_u32 v98, s1, v23, v5
	v_mul_lo_u32 v11, v20, s0
	v_mul_lo_u32 v12, v21, s0
	v_mul_lo_u32 v13, v92, s0
	v_mul_lo_u32 v14, v16, s0
	v_mul_lo_u32 v7, v7, s0
	v_add3_u32 v100, s1, v99, v5
	v_readlane_b32 s0, v253, 54
	v_readlane_b32 s13, v252, 23
	s_add_u32 s8, s12, s10
	v_ashrrev_i32_e32 v3, 31, v2
	v_readlane_b32 s1, v253, 55
	s_addc_u32 s9, s13, s11
	s_movk_i32 s82, 0xe00
	v_lshl_add_u64 v[80:81], s[0:1], 0, v[8:9]
	v_lshl_add_u64 v[82:83], v[2:3], 1, s[0:1]
	v_readlane_b32 s0, v255, 0
	v_lshl_add_u64 v[60:61], s[30:31], 0, v[8:9]
	v_lshl_add_u64 v[62:63], s[34:35], 0, v[8:9]
	v_lshl_add_u64 v[64:65], s[24:25], 0, v[8:9]
	v_lshl_add_u64 v[66:67], s[28:29], 0, v[8:9]
	v_lshl_add_u64 v[68:69], s[84:85], 0, v[8:9]
	v_lshl_add_u64 v[78:79], v[2:3], 2, s[8:9]
	v_add_u32_e32 v101, s0, v16
	v_add_u32_e32 v102, s0, v92
	v_add_u32_e32 v103, s0, v21
	v_add_u32_e32 v104, s0, v20
	v_add_u32_e32 v105, s5, v6
	s_mov_b32 s2, 0
	v_add_u32_e32 v106, v4, v11
	v_add_u32_e32 v107, v4, v12
	v_add_u32_e32 v108, v4, v13
	v_add_u32_e32 v109, v4, v14
	v_add_u32_e32 v110, v10, v7
	s_mov_b32 s5, s68
	s_mov_b32 s10, 0x3c800000
	v_readlane_b32 s14, v252, 24
	v_readlane_b32 s15, v252, 25
	v_readlane_b32 s16, v252, 26
	v_readlane_b32 s17, v252, 27
	v_readlane_b32 s18, v252, 28
	v_readlane_b32 s19, v252, 29
	v_readlane_b32 s20, v252, 30
	v_readlane_b32 s21, v252, 31
	global_load_dwordx4 v[140:143], v[56:57], off
	global_load_dwordx4 v[144:147], v[58:59], off
	global_load_dwordx4 v[148:151], v[78:79], off
	global_load_dwordx4 v[152:155], v[78:79], off offset:64
	s_branch .LBB0_1343
.LBB0_1342:
	v_add_u32_e32 v96, v1, v99
	v_add_u32_e32 v97, v1, v23
	s_waitcnt lgkmcnt(0)
	s_barrier
	ds_read_b128 v[2:5], v96
	ds_read_b128 v[6:9], v97
	ds_read_b128 v[10:13], v110
	ds_read_b128 v[14:17], v110 offset:8448
	s_waitcnt lgkmcnt(1)
	v_mfma_f32_16x16x32_bf16 v[18:21], v[10:13], v[2:5], 0
	s_andn2_b64 vcc, exec, s[0:1]
	s_waitcnt lgkmcnt(0)
	v_mfma_f32_16x16x32_bf16 v[2:5], v[14:17], v[2:5], 0
	v_mfma_f32_16x16x32_bf16 v[10:13], v[10:13], v[6:9], 0
	v_mfma_f32_16x16x32_bf16 v[6:9], v[14:17], v[6:9], 0
	ds_read_b128 v[14:17], v96 offset:64
	ds_read_b128 v[92:95], v97 offset:64
	ds_read_b128 v[112:115], v110 offset:64
	ds_read_b128 v[116:119], v110 offset:8512
	s_waitcnt lgkmcnt(1)
	v_mfma_f32_16x16x32_bf16 v[18:21], v[112:115], v[14:17], v[18:21]
	s_waitcnt lgkmcnt(0)
	v_mfma_f32_16x16x32_bf16 v[2:5], v[116:119], v[14:17], v[2:5]
	v_mfma_f32_16x16x32_bf16 v[10:13], v[112:115], v[92:95], v[10:13]
	v_mfma_f32_16x16x32_bf16 v[6:9], v[116:119], v[92:95], v[6:9]
	ds_read_b128 v[14:17], v96 offset:128
	ds_read_b128 v[92:95], v97 offset:128
	ds_read_b128 v[112:115], v110 offset:128
	ds_read_b128 v[116:119], v110 offset:8576
	s_waitcnt lgkmcnt(1)
	v_mfma_f32_16x16x32_bf16 v[18:21], v[112:115], v[14:17], v[18:21]
	s_waitcnt lgkmcnt(0)
	v_mfma_f32_16x16x32_bf16 v[2:5], v[116:119], v[14:17], v[2:5]
	v_mfma_f32_16x16x32_bf16 v[10:13], v[112:115], v[92:95], v[10:13]
	v_mfma_f32_16x16x32_bf16 v[6:9], v[116:119], v[92:95], v[6:9]
	ds_read_b128 v[14:17], v96 offset:192
	ds_read_b128 v[92:95], v97 offset:192
	ds_read_b128 v[112:115], v110 offset:192
	ds_read_b128 v[116:119], v110 offset:8640
	s_waitcnt lgkmcnt(1)
	v_mfma_f32_16x16x32_bf16 v[18:21], v[112:115], v[14:17], v[18:21]
	s_waitcnt lgkmcnt(0)
	v_mfma_f32_16x16x32_bf16 v[2:5], v[116:119], v[14:17], v[2:5]
	v_mfma_f32_16x16x32_bf16 v[10:13], v[112:115], v[92:95], v[10:13]
	v_mfma_f32_16x16x32_bf16 v[6:9], v[116:119], v[92:95], v[6:9]
	ds_read_b128 v[14:17], v96 offset:256
	ds_read_b128 v[92:95], v97 offset:256
	ds_read_b128 v[112:115], v110 offset:256
	ds_read_b128 v[116:119], v110 offset:8704
	s_waitcnt lgkmcnt(1)
	v_mfma_f32_16x16x32_bf16 v[18:21], v[112:115], v[14:17], v[18:21]
	s_waitcnt lgkmcnt(0)
	v_mfma_f32_16x16x32_bf16 v[2:5], v[116:119], v[14:17], v[2:5]
	v_mfma_f32_16x16x32_bf16 v[10:13], v[112:115], v[92:95], v[10:13]
	v_mfma_f32_16x16x32_bf16 v[6:9], v[116:119], v[92:95], v[6:9]
	ds_read_b128 v[14:17], v96 offset:320
	ds_read_b128 v[92:95], v97 offset:320
	ds_read_b128 v[112:115], v110 offset:320
	ds_read_b128 v[116:119], v110 offset:8768
	s_waitcnt lgkmcnt(1)
	v_mfma_f32_16x16x32_bf16 v[18:21], v[112:115], v[14:17], v[18:21]
	s_waitcnt lgkmcnt(0)
	v_mfma_f32_16x16x32_bf16 v[2:5], v[116:119], v[14:17], v[2:5]
	v_mfma_f32_16x16x32_bf16 v[10:13], v[112:115], v[92:95], v[10:13]
	v_mfma_f32_16x16x32_bf16 v[6:9], v[116:119], v[92:95], v[6:9]
	ds_read_b128 v[14:17], v96 offset:384
	ds_read_b128 v[92:95], v97 offset:384
	ds_read_b128 v[112:115], v110 offset:384
	ds_read_b128 v[116:119], v110 offset:8832
	s_waitcnt lgkmcnt(1)
	v_mfma_f32_16x16x32_bf16 v[18:21], v[112:115], v[14:17], v[18:21]
	s_waitcnt lgkmcnt(0)
	v_mfma_f32_16x16x32_bf16 v[2:5], v[116:119], v[14:17], v[2:5]
	v_mfma_f32_16x16x32_bf16 v[14:17], v[112:115], v[92:95], v[10:13]
	v_mfma_f32_16x16x32_bf16 v[92:95], v[116:119], v[92:95], v[6:9]
	s_nop 2
	ds_read_b128 v[6:9], v96 offset:448
	ds_read_b128 v[112:115], v97 offset:448
	ds_read_b128 v[116:119], v110 offset:448
	ds_read_b128 v[120:123], v110 offset:8896
	s_waitcnt lgkmcnt(1)
	v_mfma_f32_16x16x32_bf16 v[18:21], v[116:119], v[6:9], v[18:21]
	s_waitcnt lgkmcnt(0)
	v_mfma_f32_16x16x32_bf16 v[10:13], v[120:123], v[6:9], v[2:5]
	v_mfma_f32_16x16x32_bf16 v[6:9], v[116:119], v[112:115], v[14:17]
	v_mfma_f32_16x16x32_bf16 v[2:5], v[120:123], v[112:115], v[92:95]
	v_mov_b32_e32 v112, v148
	v_mov_b32_e32 v113, v149
	v_mov_b32_e32 v114, v150
	v_mov_b32_e32 v115, v151
	s_nop 0
	ds_read2_b64 v[14:17], v100 offset1:4
	s_waitcnt lgkmcnt(0)
; __device__ __forceinline__ float lo2f(unsigned w) { return __uint_as_float(w << 16); }
; __device__ __forceinline__ float hi2f(unsigned w) { return __uint_as_float(w & 0xffff0000u); }
; __device__ __forceinline__ float sigm(float x) { return __builtin_amdgcn_rcpf(1.f + __expf(-x)); }
; __device__ __forceinline__ void phase_fin(const Params& p, int l, int Mrows, char* smem) {
;     ...
; #pragma unroll
;     for (int m = 0; m < 2; ++m)
; #pragma unroll
;       for (int n = 0; n < 2; ++n) {
;         const int rr = m * 16 + fr, col = wid * 32 + n * 16 + fq * 4;
;         const uint2 yv = *reinterpret_cast<const uint2*>(At + rr * 264 + col);
;         const float4 b4 = *reinterpret_cast<const float4*>(glb + col);
;         uint2 w;
;         w.x = pack2(lo2f(yv.x) * sigm(acc[m][n][0] + b4.x), hi2f(yv.x) * sigm(acc[m][n][1] + b4.y));
;         w.y = pack2(lo2f(yv.y) * sigm(acc[m][n][2] + b4.z), hi2f(yv.y) * sigm(acc[m][n][3] + b4.w));
;         *reinterpret_cast<uint2*>(Y + (size_t)(r0 + rr) * 1024 + col) = w;
;       }
	v_lshlrev_b32_e32 v96, 16, v14
	v_and_b32_e32 v97, 0xffff0000, v14
	v_add_u32_e32 v92, s2, v105
	v_ashrrev_i32_e32 v93, 31, v92
	v_lshlrev_b64 v[94:95], 11, v[92:93]
	s_add_i32 s2, s2, s60
	v_add_f32_e32 v18, v18, v112
	v_add_f32_e32 v14, v19, v113
	v_mul_f32_e32 v18, 0xbfb8aa3b, v18
	v_mul_f32_e32 v14, 0xbfb8aa3b, v14
	v_exp_f32_e32 v18, v18
	v_exp_f32_e32 v14, v14
	v_add_f32_e32 v18, 1.0, v18
	v_add_f32_e32 v14, 1.0, v14
	v_rcp_f32_e32 v18, v18
	v_rcp_f32_e32 v19, v14
	v_lshlrev_b32_e32 v14, 16, v15
	v_and_b32_e32 v15, 0xffff0000, v15
	v_pk_mul_f32 v[18:19], v[18:19], v[96:97]
	s_nop 0
	v_cvt_pk_bf16_f32 v18, v18, v19
	v_add_f32_e32 v19, v20, v114
	v_mul_f32_e32 v19, 0xbfb8aa3b, v19
	v_exp_f32_e32 v19, v19
	s_nop 0
	v_add_f32_e32 v19, 1.0, v19
	v_rcp_f32_e32 v20, v19
	v_add_f32_e32 v19, v21, v115
	v_mul_f32_e32 v19, 0xbfb8aa3b, v19
	v_exp_f32_e32 v19, v19
	s_nop 0
	v_add_f32_e32 v19, 1.0, v19
	v_rcp_f32_e32 v21, v19
	s_nop 0
	v_pk_mul_f32 v[14:15], v[20:21], v[14:15]
	s_nop 0
	v_cvt_pk_bf16_f32 v19, v14, v15
	v_lshl_add_u64 v[14:15], v[82:83], 0, v[94:95]
	global_store_dwordx2 v[14:15], v[18:19], off
	v_mov_b32_e32 v18, v152
	v_mov_b32_e32 v19, v153
	v_mov_b32_e32 v20, v154
	v_mov_b32_e32 v21, v155
	v_lshlrev_b32_e32 v94, 16, v16
	v_and_b32_e32 v95, 0xffff0000, v16
	v_lshlrev_b32_e32 v16, 16, v17
	v_and_b32_e32 v17, 0xffff0000, v17
	v_add_f32_e32 v10, v10, v18
	v_add_f32_e32 v11, v11, v19
	v_mul_f32_e32 v10, 0xbfb8aa3b, v10
	v_mul_f32_e32 v11, 0xbfb8aa3b, v11
	v_exp_f32_e32 v10, v10
	v_exp_f32_e32 v11, v11
	v_add_f32_e32 v10, 1.0, v10
	v_add_f32_e32 v11, 1.0, v11
	v_rcp_f32_e32 v10, v10
	v_rcp_f32_e32 v11, v11
	s_nop 0
	v_pk_mul_f32 v[10:11], v[10:11], v[94:95]
	s_nop 0
	v_cvt_pk_bf16_f32 v10, v10, v11
	v_add_f32_e32 v11, v12, v20
	v_mul_f32_e32 v11, 0xbfb8aa3b, v11
	v_exp_f32_e32 v11, v11
	s_nop 0
	v_add_f32_e32 v11, 1.0, v11
	v_rcp_f32_e32 v12, v11
	v_add_f32_e32 v11, v13, v21
	v_mul_f32_e32 v11, 0xbfb8aa3b, v11
	v_exp_f32_e32 v11, v11
	s_nop 0
	v_add_f32_e32 v11, 1.0, v11
	v_rcp_f32_e32 v13, v11
	s_nop 0
	v_pk_mul_f32 v[12:13], v[12:13], v[16:17]
	s_nop 0
	v_cvt_pk_bf16_f32 v11, v12, v13
	global_store_dwordx2 v[14:15], v[10:11], off offset:32
	v_mov_b32_e32 v14, v148
	v_mov_b32_e32 v15, v149
	v_mov_b32_e32 v16, v150
	v_mov_b32_e32 v17, v151
	v_add_u32_e32 v10, 16, v92
	v_ashrrev_i32_e32 v11, 31, v10
	v_lshlrev_b64 v[18:19], 11, v[10:11]
	ds_read2_b64 v[10:13], v98 offset1:4
	s_waitcnt lgkmcnt(0)
	v_lshlrev_b32_e32 v20, 16, v10
	v_and_b32_e32 v21, 0xffff0000, v10
	v_lshlrev_b32_e32 v10, 16, v11
	v_and_b32_e32 v11, 0xffff0000, v11
	v_add_f32_e32 v6, v6, v14
	v_add_f32_e32 v7, v7, v15
	v_mul_f32_e32 v6, 0xbfb8aa3b, v6
	v_mul_f32_e32 v7, 0xbfb8aa3b, v7
	v_exp_f32_e32 v6, v6
	v_exp_f32_e32 v7, v7
	v_lshlrev_b32_e32 v14, 16, v12
	v_and_b32_e32 v15, 0xffff0000, v12
	v_add_f32_e32 v6, 1.0, v6
	v_add_f32_e32 v7, 1.0, v7
	v_rcp_f32_e32 v6, v6
	v_rcp_f32_e32 v7, v7
	s_nop 0
	v_pk_mul_f32 v[6:7], v[6:7], v[20:21]
	s_nop 0
	v_cvt_pk_bf16_f32 v6, v6, v7
	v_add_f32_e32 v7, v8, v16
	v_mul_f32_e32 v7, 0xbfb8aa3b, v7
	v_exp_f32_e32 v7, v7
	s_nop 0
	v_add_f32_e32 v7, 1.0, v7
	v_rcp_f32_e32 v8, v7
	v_add_f32_e32 v7, v9, v17
	v_mul_f32_e32 v7, 0xbfb8aa3b, v7
	v_exp_f32_e32 v7, v7
	s_nop 0
	v_add_f32_e32 v7, 1.0, v7
	v_rcp_f32_e32 v9, v7
	s_nop 0
	v_pk_mul_f32 v[8:9], v[8:9], v[10:11]
	s_nop 0
	v_cvt_pk_bf16_f32 v7, v8, v9
	v_lshl_add_u64 v[10:11], v[82:83], 0, v[18:19]
	global_store_dwordx2 v[10:11], v[6:7], off
	v_mov_b32_e32 v6, v152
	v_mov_b32_e32 v7, v153
	v_mov_b32_e32 v8, v154
	v_mov_b32_e32 v9, v155
	v_add_f32_e32 v2, v2, v6
	v_add_f32_e32 v3, v3, v7
	v_mul_f32_e32 v2, 0xbfb8aa3b, v2
	v_mul_f32_e32 v3, 0xbfb8aa3b, v3
	v_exp_f32_e32 v2, v2
	v_exp_f32_e32 v3, v3
	v_lshlrev_b32_e32 v6, 16, v13
	v_and_b32_e32 v7, 0xffff0000, v13
	v_add_f32_e32 v2, 1.0, v2
	v_add_f32_e32 v3, 1.0, v3
	v_rcp_f32_e32 v2, v2
	v_rcp_f32_e32 v3, v3
	s_nop 0
	v_pk_mul_f32 v[2:3], v[2:3], v[14:15]
	s_nop 0
	v_cvt_pk_bf16_f32 v2, v2, v3
	v_add_f32_e32 v3, v4, v8
	v_mul_f32_e32 v3, 0xbfb8aa3b, v3
	v_exp_f32_e32 v3, v3
	s_nop 0
	v_add_f32_e32 v3, 1.0, v3
	v_rcp_f32_e32 v4, v3
	v_add_f32_e32 v3, v5, v9
	v_mul_f32_e32 v3, 0xbfb8aa3b, v3
	v_exp_f32_e32 v3, v3
	s_nop 0
	v_add_f32_e32 v3, 1.0, v3
	v_rcp_f32_e32 v5, v3
	s_nop 0
	v_pk_mul_f32 v[4:5], v[4:5], v[6:7]
	s_nop 0
	v_cvt_pk_bf16_f32 v3, v4, v5
	global_store_dwordx2 v[10:11], v[2:3], off offset:32
	s_cbranch_vccz .LBB0_1345
; __device__ __forceinline__ float lo2f(unsigned w) { return __uint_as_float(w << 16); }
; __device__ __forceinline__ float hi2f(unsigned w) { return __uint_as_float(w & 0xffff0000u); }
; __device__ __forceinline__ float silu_f(float x) { return x * sigm(x); }
; __device__ __forceinline__ void phase_fin(const Params& p, int l, int Mrows, char* smem) {
;     ...
;   for (int it = blockIdx.x; it < items; it += gridDim.x) {
;     const int r0 = it * 32;
;     __syncthreads();
; #pragma unroll
;     for (int k = 0; k < 4; ++k) {
;       const size_t row = (size_t)(r0 + wid + k * NW);
;       const uint2 f = gf[k], bq = gb[k], z = gz[k];
;       float o[4] = {lo2f(f.x) + lo2f(bq.x), hi2f(f.x) + hi2f(bq.x), lo2f(f.y) + lo2f(bq.y), hi2f(f.y) + hi2f(bq.y)};
;       float ss = o[0] * o[0] + o[1] * o[1] + o[2] * o[2] + o[3] * o[3];
;       ss = reduce16(ss);
;       const float rs = rsqrtf(ss * (1.f / 64.f) + EPS);
;       const float4 gn = *reinterpret_cast<const float4*>(gain + (lane & 15) * 4);
;       const float zz[4] = {lo2f(z.x), hi2f(z.x), lo2f(z.y), hi2f(z.y)};
;       const float gg[4] = {gn.x, gn.y, gn.z, gn.w};
;       float r[4];
; #pragma unroll
;       for (int i = 0; i < 4; ++i) r[i] = o[i] * rs * gg[i] * silu_f(zz[i]);
.LBB0_1343:
	s_waitcnt vmcnt(23)
	v_lshlrev_b32_e32 v2, 16, v25
	s_waitcnt vmcnt(22)
	v_lshlrev_b32_e32 v4, 16, v27
	v_and_b32_e32 v3, 0xffff0000, v25
	v_and_b32_e32 v5, 0xffff0000, v27
	s_waitcnt lgkmcnt(0)
	s_barrier
	v_pk_add_f32 v[10:11], v[2:3], v[4:5]
	global_load_dwordx4 v[2:5], v[56:57], off
	v_lshlrev_b32_e32 v14, 16, v24
	v_lshlrev_b32_e32 v16, 16, v26
	v_and_b32_e32 v15, 0xffff0000, v24
	v_and_b32_e32 v17, 0xffff0000, v26
	s_waitcnt vmcnt(22)
	v_lshlrev_b32_e32 v18, 16, v28
	v_and_b32_e32 v19, 0xffff0000, v28
	v_pk_add_f32 v[14:15], v[14:15], v[16:17]
	v_mul_f32_e32 v16, 0xbfb8aa3b, v18
	v_mul_f32_e32 v17, 0xbfb8aa3b, v19
	v_exp_f32_e32 v16, v16
	v_exp_f32_e32 v17, v17
	v_add_u32_e32 v8, s2, v22
	v_ashrrev_i32_e32 v9, 31, v8
	v_add_f32_e32 v16, 1.0, v16
	v_add_f32_e32 v17, 1.0, v17
	v_rcp_f32_e32 v16, v16
	v_rcp_f32_e32 v17, v17
	s_waitcnt vmcnt(16)
	v_lshlrev_b32_e32 v118, 16, v41
	v_and_b32_e32 v119, 0xffff0000, v41
	v_lshlrev_b32_e32 v116, 16, v40
	v_pk_mul_f32 v[18:19], v[16:17], v[18:19]
	v_lshlrev_b64 v[16:17], 11, v[8:9]
	v_mul_f32_e32 v9, 0xbfb8aa3b, v118
	v_exp_f32_e32 v9, v9
	v_lshlrev_b32_e32 v12, 16, v29
	v_and_b32_e32 v13, 0xffff0000, v29
	v_mul_f32_e32 v20, 0xbfb8aa3b, v12
	v_add_f32_e32 v9, 1.0, v9
	v_rcp_f32_e32 v120, v9
	v_mul_f32_e32 v9, 0xbfb8aa3b, v119
	v_exp_f32_e32 v9, v9
	v_mul_f32_e32 v21, 0xbfb8aa3b, v13
	v_and_b32_e32 v117, 0xffff0000, v40
	v_exp_f32_e32 v20, v20
	v_add_f32_e32 v9, 1.0, v9
	v_rcp_f32_e32 v121, v9
	v_mul_f32_e32 v9, 0xbfb8aa3b, v116
	v_exp_f32_e32 v9, v9
	v_exp_f32_e32 v21, v21
	v_pk_mul_f32 v[118:119], v[120:121], v[118:119]
	v_add_f32_e32 v20, 1.0, v20
	v_add_f32_e32 v9, 1.0, v9
	v_rcp_f32_e32 v120, v9
	v_mul_f32_e32 v9, 0xbfb8aa3b, v117
	v_exp_f32_e32 v9, v9
	v_add_f32_e32 v21, 1.0, v21
	v_rcp_f32_e32 v20, v20
	v_rcp_f32_e32 v21, v21
	v_add_f32_e32 v9, 1.0, v9
	v_rcp_f32_e32 v121, v9
	v_lshlrev_b32_e32 v94, 16, v36
	v_lshlrev_b32_e32 v96, 16, v38
	v_and_b32_e32 v95, 0xffff0000, v36
	v_and_b32_e32 v97, 0xffff0000, v38
	v_lshlrev_b32_e32 v112, 16, v37
	v_lshlrev_b32_e32 v114, 16, v39
	v_and_b32_e32 v113, 0xffff0000, v37
	v_and_b32_e32 v115, 0xffff0000, v39
	v_pk_add_f32 v[94:95], v[94:95], v[96:97]
	v_pk_mul_f32 v[12:13], v[20:21], v[12:13]
	v_pk_mul_f32 v[20:21], v[14:15], v[14:15]
	v_pk_add_f32 v[112:113], v[112:113], v[114:115]
	v_pk_mul_f32 v[96:97], v[94:95], v[94:95]
	v_pk_mul_f32 v[6:7], v[10:11], v[10:11]
	v_pk_mul_f32 v[114:115], v[112:113], v[112:113]
	v_pk_mul_f32 v[116:117], v[120:121], v[116:117]
	v_mov_b32_e32 v120, v96
	v_mov_b32_e32 v121, v20
	v_mov_b32_e32 v20, v97
	v_pk_add_f32 v[20:21], v[120:121], v[20:21]
	v_mov_b32_e32 v96, v114
	v_mov_b32_e32 v97, v6
	v_pk_add_f32 v[20:21], v[20:21], v[96:97]
	v_mov_b32_e32 v6, v115
	v_pk_add_f32 v[6:7], v[6:7], v[20:21]
	s_mov_b32 s0, 0x358637bd
	s_mov_b32 s6, 0x800000
	v_mov_b32_dpp v21, v7 quad_perm:[1,0,3,2] row_mask:0xf bank_mask:0xf bound_ctrl:1
	v_mov_b32_dpp v20, v6 quad_perm:[1,0,3,2] row_mask:0xf bank_mask:0xf bound_ctrl:1
	v_pk_add_f32 v[6:7], v[6:7], v[20:21]
	v_lshl_add_u64 v[92:93], v[80:81], 0, v[16:17]
	v_add_u32_e32 v16, 8, v8
	v_mov_b32_dpp v21, v7 quad_perm:[2,3,0,1] row_mask:0xf bank_mask:0xf bound_ctrl:1
	v_mov_b32_dpp v20, v6 quad_perm:[2,3,0,1] row_mask:0xf bank_mask:0xf bound_ctrl:1
	v_pk_add_f32 v[6:7], v[6:7], v[20:21]
	v_ashrrev_i32_e32 v17, 31, v16
	s_waitcnt vmcnt(5)
	v_lshlrev_b32_e32 v114, 16, v76
	v_mov_b32_dpp v21, v7 row_half_mirror row_mask:0xf bank_mask:0xf bound_ctrl:1
	v_mov_b32_dpp v20, v6 row_half_mirror row_mask:0xf bank_mask:0xf bound_ctrl:1
	v_pk_add_f32 v[6:7], v[6:7], v[20:21]
	v_and_b32_e32 v115, 0xffff0000, v76
	s_add_i32 s5, s5, s78
	v_mov_b32_dpp v21, v7 row_mirror row_mask:0xf bank_mask:0xf bound_ctrl:1
	v_mov_b32_dpp v20, v6 row_mirror row_mask:0xf bank_mask:0xf bound_ctrl:1
	v_pk_add_f32 v[20:21], v[6:7], v[20:21]
	v_mov_b64_e32 v[6:7], s[0:1]
	v_pk_fma_f32 v[20:21], v[20:21], s[10:11], v[6:7] op_sel_hi:[1,0,0]
	s_cmp_ge_i32 s5, s4
	v_mul_f32_e32 v9, 0x4b800000, v21
	v_cmp_gt_f32_e64 s[0:1], s6, v21
	v_cmp_gt_f32_e32 vcc, s6, v20
	s_nop 0
	v_cndmask_b32_e64 v9, v21, v9, s[0:1]
	v_rsq_f32_e32 v9, v9
	s_nop 0
	v_mul_f32_e32 v21, 0x45800000, v9
	v_cndmask_b32_e64 v96, v9, v21, s[0:1]
	v_pk_mul_f32 v[14:15], v[14:15], v[96:97] op_sel_hi:[1,0]
	v_pk_mul_f32 v[10:11], v[10:11], v[96:97] op_sel_hi:[1,0]
	s_waitcnt vmcnt(0)
; __device__ __forceinline__ float lo2f(unsigned w) { return __uint_as_float(w << 16); }
; __device__ __forceinline__ float hi2f(unsigned w) { return __uint_as_float(w & 0xffff0000u); }
; __device__ __forceinline__ float silu_f(float x) { return x * sigm(x); }
; __device__ __forceinline__ void phase_fin(const Params& p, int l, int Mrows, char* smem) {
;     ...
;     for (int k = 0; k < 4; ++k) {
;       const size_t row = (size_t)(r0 + wid + k * NW);
;       const uint2 f = gf[k], bq = gb[k], z = gz[k];
;       float o[4] = {lo2f(f.x) + lo2f(bq.x), hi2f(f.x) + hi2f(bq.x), lo2f(f.y) + lo2f(bq.y), hi2f(f.y) + hi2f(bq.y)};
;       float ss = o[0] * o[0] + o[1] * o[1] + o[2] * o[2] + o[3] * o[3];
;       ss = reduce16(ss);
;       const float rs = rsqrtf(ss * (1.f / 64.f) + EPS);
;       const float4 gn = *reinterpret_cast<const float4*>(gain + (lane & 15) * 4);
;       const float zz[4] = {lo2f(z.x), hi2f(z.x), lo2f(z.y), hi2f(z.y)};
;       const float gg[4] = {gn.x, gn.y, gn.z, gn.w};
;       float r[4];
; #pragma unroll
;       for (int i = 0; i < 4; ++i) r[i] = o[i] * rs * gg[i] * silu_f(zz[i]);
;       uint2 w;
;       w.x = pack2(r[0], r[1]); w.y = pack2(r[2], r[3]);
;       *reinterpret_cast<uint2*>(Y + row * 1024 + 512 + lane * 4) = w;
;     }
	v_pk_mul_f32 v[2:3], v[2:3], v[14:15]
	v_pk_mul_f32 v[4:5], v[4:5], v[10:11]
	v_pk_mul_f32 v[2:3], v[18:19], v[2:3]
	v_pk_mul_f32 v[4:5], v[12:13], v[4:5]
	v_cvt_pk_bf16_f32 v2, v2, v3
	v_cvt_pk_bf16_f32 v3, v4, v5
	global_store_dwordx2 v[92:93], v[2:3], off offset:1024
	v_mov_b32_e32 v2, v140
	v_mov_b32_e32 v3, v141
	v_mov_b32_e32 v4, v142
	v_mov_b32_e32 v5, v143
	v_mul_f32_e32 v9, 0x4b800000, v20
	v_cndmask_b32_e32 v9, v20, v9, vcc
	v_rsq_f32_e32 v9, v9
	v_lshlrev_b32_e32 v14, 16, v53
	v_and_b32_e32 v15, 0xffff0000, v53
	v_lshlrev_b32_e32 v18, 16, v48
	v_mul_f32_e32 v10, 0x45800000, v9
	v_cndmask_b32_e32 v10, v9, v10, vcc
	v_pk_mul_f32 v[12:13], v[94:95], v[10:11] op_sel_hi:[1,0]
	v_pk_mul_f32 v[10:11], v[112:113], v[10:11] op_sel_hi:[1,0]
	v_mul_f32_e32 v9, 0xbfb8aa3b, v14
	v_exp_f32_e32 v9, v9
	v_lshlrev_b32_e32 v94, 16, v52
	v_lshlrev_b32_e32 v20, 16, v50
	v_and_b32_e32 v19, 0xffff0000, v48
	v_add_f32_e32 v9, 1.0, v9
	v_rcp_f32_e32 v92, v9
	v_mul_f32_e32 v9, 0xbfb8aa3b, v15
	v_exp_f32_e32 v9, v9
	v_and_b32_e32 v21, 0xffff0000, v50
	v_and_b32_e32 v95, 0xffff0000, v52
	v_pk_add_f32 v[18:19], v[18:19], v[20:21]
	v_add_f32_e32 v9, 1.0, v9
	v_rcp_f32_e32 v93, v9
	v_mul_f32_e32 v9, 0xbfb8aa3b, v94
	v_exp_f32_e32 v9, v9
	v_lshlrev_b32_e32 v96, 16, v77
	v_and_b32_e32 v97, 0xffff0000, v77
	v_lshlrev_b32_e32 v112, 16, v74
	v_add_f32_e32 v9, 1.0, v9
	v_rcp_f32_e32 v20, v9
	v_mul_f32_e32 v9, 0xbfb8aa3b, v95
	v_exp_f32_e32 v9, v9
	v_and_b32_e32 v113, 0xffff0000, v74
	v_pk_add_f32 v[112:113], v[112:113], v[114:115]
	v_pk_mul_f32 v[14:15], v[92:93], v[14:15]
	v_add_f32_e32 v9, 1.0, v9
	v_rcp_f32_e32 v21, v9
	v_pk_mul_f32 v[92:93], v[18:19], v[18:19]
	v_pk_mul_f32 v[114:115], v[112:113], v[112:113]
	v_pk_mul_f32 v[20:21], v[20:21], v[94:95]
	v_lshlrev_b32_e32 v94, 16, v75
	v_and_b32_e32 v95, 0xffff0000, v75
	v_pk_add_f32 v[94:95], v[94:95], v[96:97]
	v_pk_mul_f32 v[2:3], v[2:3], v[12:13]
	v_pk_mul_f32 v[4:5], v[4:5], v[10:11]
	v_pk_mul_f32 v[2:3], v[116:117], v[2:3]
	v_pk_mul_f32 v[4:5], v[118:119], v[4:5]
	v_cvt_pk_bf16_f32 v2, v2, v3
	v_cvt_pk_bf16_f32 v3, v4, v5
	v_lshlrev_b64 v[4:5], 11, v[16:17]
	v_lshl_add_u64 v[4:5], v[80:81], 0, v[4:5]
	global_store_dwordx2 v[4:5], v[2:3], off offset:1024
	v_lshlrev_b32_e32 v2, 16, v49
	v_lshlrev_b32_e32 v4, 16, v51
	v_and_b32_e32 v3, 0xffff0000, v49
	v_and_b32_e32 v5, 0xffff0000, v51
	v_pk_add_f32 v[10:11], v[2:3], v[4:5]
	v_mov_b32_e32 v2, v140
	v_mov_b32_e32 v3, v141
	v_mov_b32_e32 v4, v142
	v_mov_b32_e32 v5, v143
	v_lshlrev_b32_e32 v118, 16, v85
	v_and_b32_e32 v119, 0xffff0000, v85
	v_mul_f32_e32 v96, 0xbfb8aa3b, v118
	v_mul_f32_e32 v97, 0xbfb8aa3b, v119
	v_exp_f32_e32 v96, v96
	v_exp_f32_e32 v97, v97
	v_lshlrev_b32_e32 v116, 16, v84
	v_mul_f32_e32 v111, 0xbfb8aa3b, v116
	v_add_f32_e32 v96, 1.0, v96
	v_add_f32_e32 v97, 1.0, v97
	v_exp_f32_e32 v111, v111
	v_rcp_f32_e32 v96, v96
	v_rcp_f32_e32 v97, v97
	v_and_b32_e32 v117, 0xffff0000, v84
	v_add_f32_e32 v111, 1.0, v111
	v_pk_mul_f32 v[12:13], v[10:11], v[10:11]
	v_pk_mul_f32 v[96:97], v[96:97], v[118:119]
	v_rcp_f32_e32 v118, v111
	v_mul_f32_e32 v111, 0xbfb8aa3b, v117
	v_exp_f32_e32 v111, v111
	v_pk_mul_f32 v[120:121], v[94:95], v[94:95]
	v_add_u32_e32 v16, 16, v8
	v_ashrrev_i32_e32 v17, 31, v16
	v_add_f32_e32 v111, 1.0, v111
	v_rcp_f32_e32 v119, v111
	v_lshlrev_b64 v[16:17], 11, v[16:17]
	v_lshl_add_u64 v[16:17], v[80:81], 0, v[16:17]
	v_add_u32_e32 v8, 24, v8
	v_pk_mul_f32 v[116:117], v[118:119], v[116:117]
	v_mov_b32_e32 v118, v114
	v_mov_b32_e32 v119, v92
	v_mov_b32_e32 v92, v115
	v_pk_add_f32 v[92:93], v[118:119], v[92:93]
	v_mov_b32_e32 v114, v120
	v_mov_b32_e32 v115, v12
	v_pk_add_f32 v[92:93], v[92:93], v[114:115]
	v_mov_b32_e32 v12, v121
	v_pk_add_f32 v[12:13], v[12:13], v[92:93]
	v_ashrrev_i32_e32 v9, 31, v8
	s_nop 0
	v_mov_b32_dpp v93, v13 quad_perm:[1,0,3,2] row_mask:0xf bank_mask:0xf bound_ctrl:1
	v_mov_b32_dpp v92, v12 quad_perm:[1,0,3,2] row_mask:0xf bank_mask:0xf bound_ctrl:1
	v_pk_add_f32 v[12:13], v[12:13], v[92:93]
	s_nop 1
	v_mov_b32_dpp v93, v13 quad_perm:[2,3,0,1] row_mask:0xf bank_mask:0xf bound_ctrl:1
	v_mov_b32_dpp v92, v12 quad_perm:[2,3,0,1] row_mask:0xf bank_mask:0xf bound_ctrl:1
	v_pk_add_f32 v[12:13], v[12:13], v[92:93]
	s_nop 1
	v_mov_b32_dpp v93, v13 row_half_mirror row_mask:0xf bank_mask:0xf bound_ctrl:1
	v_mov_b32_dpp v92, v12 row_half_mirror row_mask:0xf bank_mask:0xf bound_ctrl:1
	v_pk_add_f32 v[12:13], v[12:13], v[92:93]
	s_nop 1
	v_mov_b32_dpp v93, v13 row_mirror row_mask:0xf bank_mask:0xf bound_ctrl:1
	v_mov_b32_dpp v92, v12 row_mirror row_mask:0xf bank_mask:0xf bound_ctrl:1
	v_pk_add_f32 v[12:13], v[12:13], v[92:93]
	s_nop 0
	v_pk_fma_f32 v[6:7], v[12:13], s[10:11], v[6:7] op_sel_hi:[1,0,0]
	s_nop 0
	v_mul_f32_e32 v12, 0x4b800000, v7
	v_cmp_gt_f32_e64 s[0:1], s6, v7
	v_cmp_gt_f32_e32 vcc, s6, v6
	s_nop 0
	v_cndmask_b32_e64 v7, v7, v12, s[0:1]
	v_rsq_f32_e32 v7, v7
	s_nop 0
	v_mul_f32_e32 v12, 0x45800000, v7
	v_cndmask_b32_e64 v12, v7, v12, s[0:1]
	v_pk_mul_f32 v[18:19], v[18:19], v[12:13] op_sel_hi:[1,0]
	v_pk_mul_f32 v[10:11], v[10:11], v[12:13] op_sel_hi:[1,0]
	v_mul_f32_e32 v7, 0x4b800000, v6
	v_cndmask_b32_e32 v6, v6, v7, vcc
	v_rsq_f32_e32 v6, v6
	v_lshlrev_b32_e32 v12, 16, v33
	v_and_b32_e32 v13, 0xffff0000, v33
	v_pk_mul_f32 v[2:3], v[2:3], v[18:19]
	v_pk_mul_f32 v[4:5], v[4:5], v[10:11]
	v_pk_mul_f32 v[2:3], v[20:21], v[2:3]
	v_pk_mul_f32 v[4:5], v[14:15], v[4:5]
	v_cvt_pk_bf16_f32 v2, v2, v3
	v_cvt_pk_bf16_f32 v3, v4, v5
	global_store_dwordx2 v[16:17], v[2:3], off offset:1024
	v_mov_b32_e32 v2, v140
	v_mov_b32_e32 v3, v141
	v_mov_b32_e32 v4, v142
	v_mov_b32_e32 v5, v143
	v_mul_f32_e32 v7, 0x45800000, v6
; __device__ __forceinline__ float lo2f(unsigned w) { return __uint_as_float(w << 16); }
; __device__ __forceinline__ float hi2f(unsigned w) { return __uint_as_float(w & 0xffff0000u); }
; __device__ __forceinline__ float silu_f(float x) { return x * sigm(x); }
; __device__ __forceinline__ float gelu_t(float x) { return x * sigm(1.5957691216057308f * (x + 0.044715f * x * x * x)); }
; __device__ __forceinline__ void phase_fin(const Params& p, int l, int Mrows, char* smem) {
;     ...
;       for (int i = 0; i < 4; ++i) r[i] = o[i] * rs * gg[i] * silu_f(zz[i]);
;       uint2 w;
;       w.x = pack2(r[0], r[1]); w.y = pack2(r[2], r[3]);
;       *reinterpret_cast<uint2*>(Y + row * 1024 + 512 + lane * 4) = w;
;     }
; #pragma unroll
;     for (int k = 0; k < 4; ++k) {
;       const int e = tid + k * NT, rr = e >> 6, c4 = (e & 63) * 4;
;       const uint2 f = yf[k], bq = yb[k], u = yu[k];
;       const float4 d4 = *reinterpret_cast<const float4*>(dsk + c4);
;       const float y0 = gelu_t(lo2f(f.x) + lo2f(bq.x) + d4.x * lo2f(u.x));
;       const float y1 = gelu_t(hi2f(f.x) + hi2f(bq.x) + d4.y * hi2f(u.x));
;       const float y2 = gelu_t(lo2f(f.y) + lo2f(bq.y) + d4.z * lo2f(u.y));
;       const float y3 = gelu_t(hi2f(f.y) + hi2f(bq.y) + d4.w * hi2f(u.y));
;       uint2 w;
;       w.x = pack2(y0, y1); w.y = pack2(y2, y3);
;       *reinterpret_cast<uint2*>(At + rr * 264 + c4) = w;
;     }
	v_cndmask_b32_e32 v6, v6, v7, vcc
	v_pk_mul_f32 v[10:11], v[112:113], v[6:7] op_sel_hi:[1,0]
	v_pk_mul_f32 v[6:7], v[94:95], v[6:7] op_sel_hi:[1,0]
	v_lshlrev_b32_e32 v14, 16, v35
	v_and_b32_e32 v15, 0xffff0000, v35
	v_lshlrev_b32_e32 v16, 16, v31
	v_and_b32_e32 v17, 0xffff0000, v31
	s_cselect_b64 s[0:1], -1, 0
	s_and_b64 vcc, exec, s[0:1]
	v_pk_mul_f32 v[2:3], v[2:3], v[10:11]
	v_pk_mul_f32 v[4:5], v[4:5], v[6:7]
	v_pk_mul_f32 v[2:3], v[116:117], v[2:3]
	v_pk_mul_f32 v[4:5], v[96:97], v[4:5]
	v_cvt_pk_bf16_f32 v2, v2, v3
	v_cvt_pk_bf16_f32 v3, v4, v5
	v_lshlrev_b64 v[4:5], 11, v[8:9]
	v_lshl_add_u64 v[4:5], v[80:81], 0, v[4:5]
	global_store_dwordx2 v[4:5], v[2:3], off offset:1024
	v_mov_b32_e32 v2, v144
	v_mov_b32_e32 v3, v145
	v_mov_b32_e32 v4, v146
	v_mov_b32_e32 v5, v147
	v_lshlrev_b32_e32 v6, 16, v32
	v_lshlrev_b32_e32 v8, 16, v34
	v_and_b32_e32 v7, 0xffff0000, v32
	v_and_b32_e32 v9, 0xffff0000, v34
	v_lshlrev_b32_e32 v10, 16, v30
	v_and_b32_e32 v11, 0xffff0000, v30
	v_pk_add_f32 v[6:7], v[6:7], v[8:9]
	v_pk_fma_f32 v[6:7], v[2:3], v[10:11], v[6:7]
	s_nop 0
	v_mul_f32_e32 v8, 0x3d372713, v6
	v_mul_f32_e32 v9, 0x3d372713, v7
	v_mul_f32_e32 v8, v6, v8
	v_mul_f32_e32 v9, v7, v9
	v_fma_f32 v8, v6, v8, v6
	v_fma_f32 v9, v7, v9, v7
	v_mul_f32_e32 v8, 0x3fcc422a, v8
	v_mul_f32_e32 v9, 0x3fcc422a, v9
	v_mul_f32_e32 v8, 0xbfb8aa3b, v8
	v_mul_f32_e32 v9, 0xbfb8aa3b, v9
	v_exp_f32_e32 v8, v8
	v_exp_f32_e32 v9, v9
	v_add_f32_e32 v8, 1.0, v8
	v_add_f32_e32 v9, 1.0, v9
	v_rcp_f32_e32 v8, v8
	v_rcp_f32_e32 v9, v9
	s_nop 0
	v_pk_mul_f32 v[6:7], v[6:7], v[8:9]
	v_pk_add_f32 v[8:9], v[12:13], v[14:15]
	v_cvt_pk_bf16_f32 v6, v6, v7
	v_pk_fma_f32 v[8:9], v[4:5], v[16:17], v[8:9]
	v_lshlrev_b32_e32 v12, 16, v43
	v_mul_f32_e32 v7, 0x3d372713, v8
	v_mul_f32_e32 v7, v8, v7
	v_fma_f32 v7, v8, v7, v8
	v_mul_f32_e32 v7, 0x3fcc422a, v7
	v_mul_f32_e32 v7, 0xbfb8aa3b, v7
	v_exp_f32_e32 v7, v7
	v_lshlrev_b32_e32 v14, 16, v45
	v_and_b32_e32 v13, 0xffff0000, v43
	v_and_b32_e32 v15, 0xffff0000, v45
	v_add_f32_e32 v7, 1.0, v7
	v_rcp_f32_e32 v10, v7
	v_mul_f32_e32 v7, 0x3d372713, v9
	v_mul_f32_e32 v7, v9, v7
	v_fma_f32 v7, v9, v7, v9
	v_mul_f32_e32 v7, 0x3fcc422a, v7
	v_mul_f32_e32 v7, 0xbfb8aa3b, v7
	v_exp_f32_e32 v7, v7
	v_lshlrev_b32_e32 v16, 16, v47
	v_and_b32_e32 v17, 0xffff0000, v47
	v_add_f32_e32 v7, 1.0, v7
	v_rcp_f32_e32 v11, v7
	s_nop 0
	v_pk_mul_f32 v[8:9], v[8:9], v[10:11]
	s_nop 0
	v_cvt_pk_bf16_f32 v7, v8, v9
	ds_write_b64 v106, v[6:7]
	v_lshlrev_b32_e32 v6, 16, v42
	v_lshlrev_b32_e32 v8, 16, v44
	v_and_b32_e32 v7, 0xffff0000, v42
	v_and_b32_e32 v9, 0xffff0000, v44
	v_lshlrev_b32_e32 v10, 16, v46
	v_and_b32_e32 v11, 0xffff0000, v46
	v_pk_add_f32 v[6:7], v[6:7], v[8:9]
	s_nop 0
	v_pk_fma_f32 v[6:7], v[2:3], v[10:11], v[6:7]
	s_nop 0
	v_mul_f32_e32 v8, 0x3d372713, v6
	v_mul_f32_e32 v9, 0x3d372713, v7
	v_mul_f32_e32 v8, v6, v8
	v_mul_f32_e32 v9, v7, v9
	v_fma_f32 v8, v6, v8, v6
	v_fma_f32 v9, v7, v9, v7
	v_mul_f32_e32 v8, 0x3fcc422a, v8
	v_mul_f32_e32 v9, 0x3fcc422a, v9
	v_mul_f32_e32 v8, 0xbfb8aa3b, v8
	v_mul_f32_e32 v9, 0xbfb8aa3b, v9
	v_exp_f32_e32 v8, v8
	v_exp_f32_e32 v9, v9
	v_add_f32_e32 v8, 1.0, v8
	v_add_f32_e32 v9, 1.0, v9
	v_rcp_f32_e32 v8, v8
	v_rcp_f32_e32 v9, v9
	s_nop 0
	v_pk_mul_f32 v[6:7], v[6:7], v[8:9]
	v_pk_add_f32 v[8:9], v[12:13], v[14:15]
	v_cvt_pk_bf16_f32 v6, v6, v7
	v_pk_fma_f32 v[8:9], v[4:5], v[16:17], v[8:9]
	v_lshlrev_b32_e32 v12, 16, v55
	v_mul_f32_e32 v7, 0x3d372713, v8
	v_mul_f32_e32 v7, v8, v7
	v_fma_f32 v7, v8, v7, v8
	v_mul_f32_e32 v7, 0x3fcc422a, v7
	v_mul_f32_e32 v7, 0xbfb8aa3b, v7
	v_exp_f32_e32 v7, v7
	v_lshlrev_b32_e32 v14, 16, v71
	v_and_b32_e32 v13, 0xffff0000, v55
	v_and_b32_e32 v15, 0xffff0000, v71
	v_add_f32_e32 v7, 1.0, v7
	v_rcp_f32_e32 v10, v7
	v_mul_f32_e32 v7, 0x3d372713, v9
	v_mul_f32_e32 v7, v9, v7
	v_fma_f32 v7, v9, v7, v9
	v_mul_f32_e32 v7, 0x3fcc422a, v7
	v_mul_f32_e32 v7, 0xbfb8aa3b, v7
	v_exp_f32_e32 v7, v7
	v_lshlrev_b32_e32 v16, 16, v73
	v_and_b32_e32 v17, 0xffff0000, v73
	v_add_f32_e32 v7, 1.0, v7
	v_rcp_f32_e32 v11, v7
	s_nop 0
	v_pk_mul_f32 v[8:9], v[8:9], v[10:11]
	s_nop 0
	v_cvt_pk_bf16_f32 v7, v8, v9
	ds_write_b64 v107, v[6:7]
	v_lshlrev_b32_e32 v6, 16, v54
	v_lshlrev_b32_e32 v8, 16, v70
	v_and_b32_e32 v7, 0xffff0000, v54
	v_and_b32_e32 v9, 0xffff0000, v70
	v_lshlrev_b32_e32 v10, 16, v72
	v_and_b32_e32 v11, 0xffff0000, v72
	v_pk_add_f32 v[6:7], v[6:7], v[8:9]
	s_nop 0
	v_pk_fma_f32 v[6:7], v[2:3], v[10:11], v[6:7]
	s_nop 0
	v_mul_f32_e32 v8, 0x3d372713, v6
	v_mul_f32_e32 v9, 0x3d372713, v7
	v_mul_f32_e32 v8, v6, v8
	v_mul_f32_e32 v9, v7, v9
	v_fma_f32 v8, v6, v8, v6
	v_fma_f32 v9, v7, v9, v7
	v_mul_f32_e32 v8, 0x3fcc422a, v8
	v_mul_f32_e32 v9, 0x3fcc422a, v9
	v_mul_f32_e32 v8, 0xbfb8aa3b, v8
	v_mul_f32_e32 v9, 0xbfb8aa3b, v9
	v_exp_f32_e32 v8, v8
	v_exp_f32_e32 v9, v9
	v_add_f32_e32 v8, 1.0, v8
	v_add_f32_e32 v9, 1.0, v9
	v_rcp_f32_e32 v8, v8
	v_rcp_f32_e32 v9, v9
	s_nop 0
	v_pk_mul_f32 v[6:7], v[6:7], v[8:9]
	v_pk_add_f32 v[8:9], v[12:13], v[14:15]
	v_cvt_pk_bf16_f32 v6, v6, v7
	v_pk_fma_f32 v[8:9], v[4:5], v[16:17], v[8:9]
	v_lshlrev_b32_e32 v14, 16, v86
; __device__ __forceinline__ float lo2f(unsigned w) { return __uint_as_float(w << 16); }
; __device__ __forceinline__ float hi2f(unsigned w) { return __uint_as_float(w & 0xffff0000u); }
; __device__ __forceinline__ float gelu_t(float x) { return x * sigm(1.5957691216057308f * (x + 0.044715f * x * x * x)); }
; __device__ __forceinline__ void phase_fin(const Params& p, int l, int Mrows, char* smem) {
;     ...
;   auto load_item = [&](int it) {
;     const int r0 = it * 32;
; #pragma unroll
;     for (int k = 0; k < 4; ++k) {
;       const size_t row = (size_t)(r0 + wid + k * NW);
;       gf[k] = *reinterpret_cast<const uint2*>(OGF + row * 256 + lane * 4);
;       gb[k] = *reinterpret_cast<const uint2*>(OGB + row * 256 + lane * 4);
;       gz[k] = *reinterpret_cast<const uint2*>(PB + row * PBW + PB_Z + lane * 4);
;       const int e = tid + k * NT, rr = e >> 6, c4 = (e & 63) * 4;
;       const size_t row2 = (size_t)(r0 + rr);
;       yf[k] = *reinterpret_cast<const uint2*>(O5F + row2 * 256 + c4);
;       yb[k] = *reinterpret_cast<const uint2*>(O5B + row2 * 256 + c4);
;       yu[k] = *reinterpret_cast<const uint2*>(PB + row2 * PBW + c4);
;     }
;     ...
; #pragma unroll
;     for (int k = 0; k < 4; ++k) {
;       const int e = tid + k * NT, rr = e >> 6, c4 = (e & 63) * 4;
;       const uint2 f = yf[k], bq = yb[k], u = yu[k];
;       const float4 d4 = *reinterpret_cast<const float4*>(dsk + c4);
;       const float y0 = gelu_t(lo2f(f.x) + lo2f(bq.x) + d4.x * lo2f(u.x));
;       const float y1 = gelu_t(hi2f(f.x) + hi2f(bq.x) + d4.y * hi2f(u.x));
;       const float y2 = gelu_t(lo2f(f.y) + lo2f(bq.y) + d4.z * lo2f(u.y));
;       const float y3 = gelu_t(hi2f(f.y) + hi2f(bq.y) + d4.w * hi2f(u.y));
;       uint2 w;
;       w.x = pack2(y0, y1); w.y = pack2(y2, y3);
;       *reinterpret_cast<uint2*>(At + rr * 264 + c4) = w;
;     }
;     if (it + (int)gridDim.x < items) load_item(it + gridDim.x);
	v_mul_f32_e32 v7, 0x3d372713, v8
	v_mul_f32_e32 v7, v8, v7
	v_fma_f32 v7, v8, v7, v8
	v_mul_f32_e32 v7, 0x3fcc422a, v7
	v_mul_f32_e32 v7, 0xbfb8aa3b, v7
	v_exp_f32_e32 v7, v7
	v_lshlrev_b32_e32 v16, 16, v88
	v_and_b32_e32 v15, 0xffff0000, v86
	v_and_b32_e32 v17, 0xffff0000, v88
	v_add_f32_e32 v7, 1.0, v7
	v_rcp_f32_e32 v10, v7
	v_mul_f32_e32 v7, 0x3d372713, v9
	v_mul_f32_e32 v7, v9, v7
	v_lshlrev_b32_e32 v12, 16, v90
	v_and_b32_e32 v13, 0xffff0000, v90
	v_pk_add_f32 v[14:15], v[14:15], v[16:17]
	v_fma_f32 v7, v9, v7, v9
	v_pk_fma_f32 v[2:3], v[2:3], v[12:13], v[14:15]
	v_mul_f32_e32 v7, 0x3fcc422a, v7
	v_mul_f32_e32 v12, 0x3d372713, v2
	v_mul_f32_e32 v13, 0x3d372713, v3
	v_mul_f32_e32 v7, 0xbfb8aa3b, v7
	v_mul_f32_e32 v12, v2, v12
	v_mul_f32_e32 v13, v3, v13
	v_exp_f32_e32 v7, v7
	v_fma_f32 v12, v2, v12, v2
	v_fma_f32 v13, v3, v13, v3
	v_mul_f32_e32 v12, 0x3fcc422a, v12
	v_mul_f32_e32 v13, 0x3fcc422a, v13
	v_mul_f32_e32 v12, 0xbfb8aa3b, v12
	v_mul_f32_e32 v13, 0xbfb8aa3b, v13
	v_exp_f32_e32 v12, v12
	v_exp_f32_e32 v13, v13
	v_add_f32_e32 v7, 1.0, v7
	v_rcp_f32_e32 v11, v7
	v_add_f32_e32 v12, 1.0, v12
	v_add_f32_e32 v13, 1.0, v13
	v_rcp_f32_e32 v12, v12
	v_rcp_f32_e32 v13, v13
	v_pk_mul_f32 v[8:9], v[8:9], v[10:11]
	v_lshlrev_b32_e32 v10, 16, v89
	v_cvt_pk_bf16_f32 v7, v8, v9
	v_lshlrev_b32_e32 v8, 16, v87
	v_and_b32_e32 v9, 0xffff0000, v87
	v_and_b32_e32 v11, 0xffff0000, v89
	ds_write_b64 v108, v[6:7]
	v_lshlrev_b32_e32 v6, 16, v91
	v_and_b32_e32 v7, 0xffff0000, v91
	v_pk_add_f32 v[8:9], v[8:9], v[10:11]
	v_pk_mul_f32 v[2:3], v[2:3], v[12:13]
	v_pk_fma_f32 v[4:5], v[4:5], v[6:7], v[8:9]
	v_cvt_pk_bf16_f32 v2, v2, v3
	v_mul_f32_e32 v3, 0x3d372713, v4
	v_mul_f32_e32 v3, v4, v3
	v_fma_f32 v3, v4, v3, v4
	v_mul_f32_e32 v3, 0x3fcc422a, v3
	v_mul_f32_e32 v3, 0xbfb8aa3b, v3
	v_exp_f32_e32 v3, v3
	s_nop 0
	v_add_f32_e32 v3, 1.0, v3
	v_rcp_f32_e32 v6, v3
	v_mul_f32_e32 v3, 0x3d372713, v5
	v_mul_f32_e32 v3, v5, v3
	v_fma_f32 v3, v5, v3, v5
	v_mul_f32_e32 v3, 0x3fcc422a, v3
	v_mul_f32_e32 v3, 0xbfb8aa3b, v3
	v_exp_f32_e32 v3, v3
	s_nop 0
	v_add_f32_e32 v3, 1.0, v3
	v_rcp_f32_e32 v7, v3
	s_nop 0
	v_pk_mul_f32 v[4:5], v[4:5], v[6:7]
	s_nop 0
	v_cvt_pk_bf16_f32 v3, v4, v5
	ds_write_b64 v109, v[2:3]
	s_cbranch_vccnz .LBB0_1342
	v_add_u32_e32 v2, s2, v104
	v_ashrrev_i32_e32 v3, 31, v2
	v_lshlrev_b64 v[4:5], 9, v[2:3]
	v_lshl_add_u64 v[6:7], v[60:61], 0, v[4:5]
	s_movk_i32 s8, 0xe00
	v_lshl_add_u64 v[8:9], v[62:63], 0, v[4:5]
	v_mad_i64_i32 v[10:11], s[6:7], v2, s8, v[68:69]
	global_load_dwordx2 v[24:25], v[6:7], off
	global_load_dwordx2 v[26:27], v[8:9], off
	global_load_dwordx2 v[28:29], v[10:11], off offset:2048
	global_load_dwordx2 v[30:31], v[10:11], off
	v_add_u32_e32 v6, 8, v2
	v_ashrrev_i32_e32 v7, 31, v6
	v_lshl_add_u64 v[12:13], v[64:65], 0, v[4:5]
	v_lshl_add_u64 v[4:5], v[66:67], 0, v[4:5]
	v_lshlrev_b64 v[8:9], 9, v[6:7]
	v_lshl_add_u64 v[10:11], v[60:61], 0, v[8:9]
	v_lshl_add_u64 v[8:9], v[62:63], 0, v[8:9]
	global_load_dwordx2 v[32:33], v[12:13], off
	global_load_dwordx2 v[34:35], v[4:5], off
	global_load_dwordx2 v[36:37], v[10:11], off
	global_load_dwordx2 v[38:39], v[8:9], off
	v_mad_i64_i32 v[4:5], s[6:7], v6, s8, v[68:69]
	v_add_u32_e32 v6, s2, v103
	v_ashrrev_i32_e32 v7, 31, v6
	v_lshlrev_b64 v[8:9], 9, v[6:7]
	v_lshl_add_u64 v[10:11], v[64:65], 0, v[8:9]
	v_lshl_add_u64 v[8:9], v[66:67], 0, v[8:9]
	v_mad_i64_i32 v[6:7], s[6:7], v6, s8, v[68:69]
	global_load_dwordx2 v[40:41], v[4:5], off offset:2048
	global_load_dwordx2 v[42:43], v[10:11], off
	global_load_dwordx2 v[44:45], v[8:9], off
	global_load_dwordx2 v[46:47], v[6:7], off
	v_add_u32_e32 v4, 16, v2
	v_ashrrev_i32_e32 v5, 31, v4
	v_add_u32_e32 v10, s2, v102
	v_lshlrev_b64 v[6:7], 9, v[4:5]
	v_ashrrev_i32_e32 v11, 31, v10
	v_add_u32_e32 v2, 24, v2
	v_lshl_add_u64 v[8:9], v[60:61], 0, v[6:7]
	v_mad_i64_i32 v[4:5], s[6:7], v4, s8, v[68:69]
	v_lshlrev_b64 v[12:13], 9, v[10:11]
	v_ashrrev_i32_e32 v3, 31, v2
	v_lshl_add_u64 v[6:7], v[62:63], 0, v[6:7]
	v_lshl_add_u64 v[14:15], v[64:65], 0, v[12:13]
	global_load_dwordx2 v[48:49], v[8:9], off
	global_load_dwordx2 v[50:51], v[6:7], off
	global_load_dwordx2 v[52:53], v[4:5], off offset:2048
	global_load_dwordx2 v[54:55], v[14:15], off
	v_lshl_add_u64 v[4:5], v[66:67], 0, v[12:13]
	v_lshlrev_b64 v[8:9], 9, v[2:3]
	v_mad_i64_i32 v[6:7], s[6:7], v10, s8, v[68:69]
	v_lshl_add_u64 v[10:11], v[60:61], 0, v[8:9]
	v_lshl_add_u64 v[8:9], v[62:63], 0, v[8:9]
	global_load_dwordx2 v[70:71], v[4:5], off
	global_load_dwordx2 v[72:73], v[6:7], off
	global_load_dwordx2 v[74:75], v[10:11], off
	global_load_dwordx2 v[76:77], v[8:9], off
	v_add_u32_e32 v4, s2, v101
	v_ashrrev_i32_e32 v5, 31, v4
	v_mad_i64_i32 v[2:3], s[6:7], v2, s8, v[68:69]
	v_lshlrev_b64 v[6:7], 9, v[4:5]
	v_lshl_add_u64 v[8:9], v[64:65], 0, v[6:7]
	v_lshl_add_u64 v[6:7], v[66:67], 0, v[6:7]
	v_mad_i64_i32 v[4:5], s[6:7], v4, s8, v[68:69]
	global_load_dwordx2 v[84:85], v[2:3], off offset:2048
	global_load_dwordx2 v[86:87], v[8:9], off
	global_load_dwordx2 v[88:89], v[6:7], off
	global_load_dwordx2 v[90:91], v[4:5], off
	s_movk_i32 s82, 0xe00
	s_branch .LBB0_1342

; __device__ __forceinline__ float lo2f(unsigned w) { return __uint_as_float(w << 16); }
; __device__ __forceinline__ float hi2f(unsigned w) { return __uint_as_float(w & 0xffff0000u); }
; __device__ __forceinline__ float sigm(float x) { return __builtin_amdgcn_rcpf(1.f + __expf(-x)); }
;   __device__ __forceinline__ void operator()(const f32x4 (&acc)[2][2][4][2], const Unit& u, int wr, int wc, int fr, int fq) const {
;     ...
;       const int q = s - 4, bjq = q >> 1, nq = q & 1;
; #pragma unroll
;       for (int ai = 0; ai < 2; ++ai)
; #pragma unroll
;         for (int m = 0; m < 4; ++m) {
;           float o[4] = {0.f, 0.f, 0.f, 0.f};
; #pragma unroll
;           for (int bj = 0; bj < 2; ++bj)
; #pragma unroll
;             for (int n = 0; n < 2; ++n) {
;               const int ib = 2 * bj + n;
;               const uint2 b2 = *(reinterpret_cast<const uint2*>(brs + (size_t)(ib * 16 + (ai * 2 + bjq) * 4 + m) * 512 + tid) + nq);
;               const f32x4 g = acc[ai][bj][m][n];
;               o[0] += sigm(g[0]) * lo2f(b2.x); o[1] += sigm(g[1]) * hi2f(b2.x);
;               o[2] += sigm(g[2]) * lo2f(b2.y); o[3] += sigm(g[3]) * hi2f(b2.y);
;             }
;           const int r = u.pm * 256 + ai * 128 + wr * 64 + m * 16 + fr;
;           const int d = dq * 256 + 64 * q + 16 * wc + 4 * fq;
;           uint2 w; w.x = pack2(o[0], o[1]); w.y = pack2(o[2], o[3]);
;           *reinterpret_cast<uint2*>(ACC + (size_t)r * 1024 + d) = w;
;         }
.LBB0_1416:
	s_add_i32 s15, s11, -4
	s_and_b32 s19, s2, 1
	s_lshl_b32 s2, s2, 5
	s_and_b32 s2, s2, 0xffffff00
	s_lshl_b32 s18, s15, 1
	s_lshl_b32 s15, s15, 6
	s_add_i32 s15, s15, s2
	s_and_b32 s14, s18, 0x7ffffffc
	s_lshl_b32 s2, s19, 3
	s_lshl_b32 s14, s14, 13
	s_add_i32 s2, s2, s14
	v_lshlrev_b32_e32 v144, 4, v140
	v_add_u32_e32 v144, s2, v144
	v_mov_b32_e32 v170, v144
	global_load_dwordx2 v[146:147], v170, s[48:49]
	v_add_u32_e32 v171, 0x20000, v144
	global_load_dwordx2 v[148:149], v171, s[48:49]
	v_add_u32_e32 v172, 0x40000, v144
	global_load_dwordx2 v[150:151], v172, s[48:49]
	v_add_u32_e32 v173, 0x60000, v144
	global_load_dwordx2 v[152:153], v173, s[48:49]
	v_add_u32_e32 v170, 0x2000, v144
	global_load_dwordx2 v[154:155], v170, s[48:49]
	v_add_u32_e32 v171, 0x22000, v144
	global_load_dwordx2 v[156:157], v171, s[48:49]
	v_add_u32_e32 v172, 0x42000, v144
	global_load_dwordx2 v[158:159], v172, s[48:49]
	v_add_u32_e32 v173, 0x62000, v144
	global_load_dwordx2 v[160:161], v173, s[48:49]
	v_add_u32_e32 v170, 0x4000, v144
	global_load_dwordx2 v[162:163], v170, s[48:49]
	v_add_u32_e32 v171, 0x24000, v144
	global_load_dwordx2 v[164:165], v171, s[48:49]
	v_add_u32_e32 v172, 0x44000, v144
	global_load_dwordx2 v[166:167], v172, s[48:49]
	v_add_u32_e32 v173, 0x64000, v144
	global_load_dwordx2 v[168:169], v173, s[48:49]
	v_or_b32_e32 v145, s15, v200
	v_lshl_add_u32 v143, s16, 8, v1
	v_lshlrev_b32_e32 v145, 1, v145
	v_lshl_add_u32 v145, v143, 11, v145
	v_mul_f32_e32 v174, 0xbfb8aa3b, v126
	v_mul_f32_e32 v175, 0xbfb8aa3b, v127
	v_mul_f32_e32 v182, 0xbfb8aa3b, v128
	v_mul_f32_e32 v183, 0xbfb8aa3b, v129
	v_exp_f32_e32 v174, v174
	v_exp_f32_e32 v175, v175
	v_exp_f32_e32 v182, v182
	v_exp_f32_e32 v183, v183
	v_add_f32_e32 v174, 1.0, v174
	v_add_f32_e32 v175, 1.0, v175
	v_add_f32_e32 v182, 1.0, v182
	v_add_f32_e32 v183, 1.0, v183
	v_rcp_f32_e32 v202, v174
	v_rcp_f32_e32 v203, v175
	v_rcp_f32_e32 v204, v182
	v_rcp_f32_e32 v205, v183
	v_mul_f32_e32 v174, 0xbfb8aa3b, v122
	v_mul_f32_e32 v175, 0xbfb8aa3b, v123
	v_mul_f32_e32 v182, 0xbfb8aa3b, v124
	v_mul_f32_e32 v183, 0xbfb8aa3b, v125
	v_exp_f32_e32 v174, v174
	v_exp_f32_e32 v175, v175
	v_exp_f32_e32 v182, v182
	v_exp_f32_e32 v183, v183
	v_add_f32_e32 v174, 1.0, v174
	v_add_f32_e32 v175, 1.0, v175
	v_add_f32_e32 v182, 1.0, v182
	v_add_f32_e32 v183, 1.0, v183
	v_rcp_f32_e32 v206, v174
	v_rcp_f32_e32 v207, v175
	v_rcp_f32_e32 v208, v182
	v_rcp_f32_e32 v209, v183
	v_mul_f32_e32 v174, 0xbfb8aa3b, v94
	v_mul_f32_e32 v175, 0xbfb8aa3b, v95
	v_mul_f32_e32 v182, 0xbfb8aa3b, v96
	v_mul_f32_e32 v183, 0xbfb8aa3b, v97
	v_exp_f32_e32 v174, v174
	v_exp_f32_e32 v175, v175
	v_exp_f32_e32 v182, v182
	v_exp_f32_e32 v183, v183
	v_add_f32_e32 v174, 1.0, v174
	v_add_f32_e32 v175, 1.0, v175
	v_add_f32_e32 v182, 1.0, v182
	v_add_f32_e32 v183, 1.0, v183
	v_rcp_f32_e32 v210, v174
	v_rcp_f32_e32 v211, v175
	v_rcp_f32_e32 v212, v182
	v_rcp_f32_e32 v213, v183
	v_mul_f32_e32 v174, 0xbfb8aa3b, v90
	v_mul_f32_e32 v175, 0xbfb8aa3b, v91
	v_mul_f32_e32 v182, 0xbfb8aa3b, v92
	v_mul_f32_e32 v183, 0xbfb8aa3b, v93
	v_exp_f32_e32 v174, v174
	v_exp_f32_e32 v175, v175
	v_exp_f32_e32 v182, v182
	v_exp_f32_e32 v183, v183
	v_add_f32_e32 v174, 1.0, v174
	v_add_f32_e32 v175, 1.0, v175
	v_add_f32_e32 v182, 1.0, v182
	v_add_f32_e32 v183, 1.0, v183
	v_rcp_f32_e32 v214, v174
	v_rcp_f32_e32 v215, v175
	v_rcp_f32_e32 v216, v182
	v_rcp_f32_e32 v217, v183
	s_waitcnt vmcnt(8)
	v_lshlrev_b32_e32 v218, 16, v146
	v_and_b32_e32 v219, 0xffff0000, v146
	v_lshlrev_b32_e32 v220, 16, v147
	v_and_b32_e32 v221, 0xffff0000, v147
	v_pk_fma_f32 v[222:223], v[202:203], v[218:219], 0 op_sel_hi:[1,1,0]
	v_pk_fma_f32 v[224:225], v[204:205], v[220:221], 0 op_sel_hi:[1,1,0]
	v_lshlrev_b32_e32 v218, 16, v148
	v_and_b32_e32 v219, 0xffff0000, v148
	v_lshlrev_b32_e32 v220, 16, v149
	v_and_b32_e32 v221, 0xffff0000, v149
	v_pk_fma_f32 v[222:223], v[206:207], v[218:219], v[222:223]
	v_pk_fma_f32 v[224:225], v[208:209], v[220:221], v[224:225]
	v_lshlrev_b32_e32 v218, 16, v150
	v_and_b32_e32 v219, 0xffff0000, v150
	v_lshlrev_b32_e32 v220, 16, v151
	v_and_b32_e32 v221, 0xffff0000, v151
	v_pk_fma_f32 v[222:223], v[210:211], v[218:219], v[222:223]
	v_pk_fma_f32 v[224:225], v[212:213], v[220:221], v[224:225]
	v_lshlrev_b32_e32 v218, 16, v152
	v_and_b32_e32 v219, 0xffff0000, v152
	v_lshlrev_b32_e32 v220, 16, v153
	v_and_b32_e32 v221, 0xffff0000, v153
	v_pk_fma_f32 v[222:223], v[214:215], v[218:219], v[222:223]
	v_pk_fma_f32 v[224:225], v[216:217], v[220:221], v[224:225]
	v_mov_b32_e32 v230, v145
	v_cvt_pk_bf16_f32 v226, v222, v223
	v_cvt_pk_bf16_f32 v227, v224, v225
	global_store_dwordx2 v230, v[226:227], s[84:85]
	v_add_u32_e32 v170, 0x6000, v144
	global_load_dwordx2 v[146:147], v170, s[48:49]
	v_add_u32_e32 v171, 0x26000, v144
	global_load_dwordx2 v[148:149], v171, s[48:49]
	v_add_u32_e32 v172, 0x46000, v144
	global_load_dwordx2 v[150:151], v172, s[48:49]
	v_add_u32_e32 v173, 0x66000, v144
	global_load_dwordx2 v[152:153], v173, s[48:49]
	v_mul_f32_e32 v174, 0xbfb8aa3b, v118
	v_mul_f32_e32 v175, 0xbfb8aa3b, v119
	v_mul_f32_e32 v182, 0xbfb8aa3b, v120
	v_mul_f32_e32 v183, 0xbfb8aa3b, v121
	v_exp_f32_e32 v174, v174
	v_exp_f32_e32 v175, v175
	v_exp_f32_e32 v182, v182
	v_exp_f32_e32 v183, v183
	v_add_f32_e32 v174, 1.0, v174
	v_add_f32_e32 v175, 1.0, v175
	v_add_f32_e32 v182, 1.0, v182
	v_add_f32_e32 v183, 1.0, v183
	v_rcp_f32_e32 v202, v174
	v_rcp_f32_e32 v203, v175
	v_rcp_f32_e32 v204, v182
	v_rcp_f32_e32 v205, v183
	v_mul_f32_e32 v174, 0xbfb8aa3b, v114
	v_mul_f32_e32 v175, 0xbfb8aa3b, v115
	v_mul_f32_e32 v182, 0xbfb8aa3b, v116
	v_mul_f32_e32 v183, 0xbfb8aa3b, v117
	v_exp_f32_e32 v174, v174
	v_exp_f32_e32 v175, v175
	v_exp_f32_e32 v182, v182
	v_exp_f32_e32 v183, v183
	v_add_f32_e32 v174, 1.0, v174
	v_add_f32_e32 v175, 1.0, v175
	v_add_f32_e32 v182, 1.0, v182
	v_add_f32_e32 v183, 1.0, v183
	v_rcp_f32_e32 v206, v174
	v_rcp_f32_e32 v207, v175
	v_rcp_f32_e32 v208, v182
	v_rcp_f32_e32 v209, v183
	v_mul_f32_e32 v174, 0xbfb8aa3b, v86
	v_mul_f32_e32 v175, 0xbfb8aa3b, v87
	v_mul_f32_e32 v182, 0xbfb8aa3b, v88
	v_mul_f32_e32 v183, 0xbfb8aa3b, v89
	v_exp_f32_e32 v174, v174
	v_exp_f32_e32 v175, v175
	v_exp_f32_e32 v182, v182
	v_exp_f32_e32 v183, v183
	v_add_f32_e32 v174, 1.0, v174
	v_add_f32_e32 v175, 1.0, v175
	v_add_f32_e32 v182, 1.0, v182
	v_add_f32_e32 v183, 1.0, v183
	v_rcp_f32_e32 v210, v174
	v_rcp_f32_e32 v211, v175
	v_rcp_f32_e32 v212, v182
	v_rcp_f32_e32 v213, v183
	v_mul_f32_e32 v174, 0xbfb8aa3b, v82
	v_mul_f32_e32 v175, 0xbfb8aa3b, v83
	v_mul_f32_e32 v182, 0xbfb8aa3b, v84
	v_mul_f32_e32 v183, 0xbfb8aa3b, v85
	v_exp_f32_e32 v174, v174
	v_exp_f32_e32 v175, v175
	v_exp_f32_e32 v182, v182
	v_exp_f32_e32 v183, v183
	v_add_f32_e32 v174, 1.0, v174
	v_add_f32_e32 v175, 1.0, v175
	v_add_f32_e32 v182, 1.0, v182
	v_add_f32_e32 v183, 1.0, v183
	v_rcp_f32_e32 v214, v174
	v_rcp_f32_e32 v215, v175
	v_rcp_f32_e32 v216, v182
	v_rcp_f32_e32 v217, v183
	s_waitcnt vmcnt(9)
; __device__ __forceinline__ float lo2f(unsigned w) { return __uint_as_float(w << 16); }
; __device__ __forceinline__ float hi2f(unsigned w) { return __uint_as_float(w & 0xffff0000u); }
; __device__ __forceinline__ float sigm(float x) { return __builtin_amdgcn_rcpf(1.f + __expf(-x)); }
;   __device__ __forceinline__ void operator()(const f32x4 (&acc)[2][2][4][2], const Unit& u, int wr, int wc, int fr, int fq) const {
;     ...
;       const int q = s - 4, bjq = q >> 1, nq = q & 1;
; #pragma unroll
;       for (int ai = 0; ai < 2; ++ai)
; #pragma unroll
;         for (int m = 0; m < 4; ++m) {
;           float o[4] = {0.f, 0.f, 0.f, 0.f};
; #pragma unroll
;           for (int bj = 0; bj < 2; ++bj)
; #pragma unroll
;             for (int n = 0; n < 2; ++n) {
;               const int ib = 2 * bj + n;
;               const uint2 b2 = *(reinterpret_cast<const uint2*>(brs + (size_t)(ib * 16 + (ai * 2 + bjq) * 4 + m) * 512 + tid) + nq);
;               const f32x4 g = acc[ai][bj][m][n];
;               o[0] += sigm(g[0]) * lo2f(b2.x); o[1] += sigm(g[1]) * hi2f(b2.x);
;               o[2] += sigm(g[2]) * lo2f(b2.y); o[3] += sigm(g[3]) * hi2f(b2.y);
;             }
;           const int r = u.pm * 256 + ai * 128 + wr * 64 + m * 16 + fr;
;           const int d = dq * 256 + 64 * q + 16 * wc + 4 * fq;
;           uint2 w; w.x = pack2(o[0], o[1]); w.y = pack2(o[2], o[3]);
;           *reinterpret_cast<uint2*>(ACC + (size_t)r * 1024 + d) = w;
;         }
	v_lshlrev_b32_e32 v218, 16, v154
	v_and_b32_e32 v219, 0xffff0000, v154
	v_lshlrev_b32_e32 v220, 16, v155
	v_and_b32_e32 v221, 0xffff0000, v155
	v_pk_fma_f32 v[222:223], v[202:203], v[218:219], 0 op_sel_hi:[1,1,0]
	v_pk_fma_f32 v[224:225], v[204:205], v[220:221], 0 op_sel_hi:[1,1,0]
	v_lshlrev_b32_e32 v218, 16, v156
	v_and_b32_e32 v219, 0xffff0000, v156
	v_lshlrev_b32_e32 v220, 16, v157
	v_and_b32_e32 v221, 0xffff0000, v157
	v_pk_fma_f32 v[222:223], v[206:207], v[218:219], v[222:223]
	v_pk_fma_f32 v[224:225], v[208:209], v[220:221], v[224:225]
	v_lshlrev_b32_e32 v218, 16, v158
	v_and_b32_e32 v219, 0xffff0000, v158
	v_lshlrev_b32_e32 v220, 16, v159
	v_and_b32_e32 v221, 0xffff0000, v159
	v_pk_fma_f32 v[222:223], v[210:211], v[218:219], v[222:223]
	v_pk_fma_f32 v[224:225], v[212:213], v[220:221], v[224:225]
	v_lshlrev_b32_e32 v218, 16, v160
	v_and_b32_e32 v219, 0xffff0000, v160
	v_lshlrev_b32_e32 v220, 16, v161
	v_and_b32_e32 v221, 0xffff0000, v161
	v_pk_fma_f32 v[222:223], v[214:215], v[218:219], v[222:223]
	v_pk_fma_f32 v[224:225], v[216:217], v[220:221], v[224:225]
	v_add_u32_e32 v231, 0x8000, v145
	v_cvt_pk_bf16_f32 v228, v222, v223
	v_cvt_pk_bf16_f32 v229, v224, v225
	global_store_dwordx2 v231, v[228:229], s[84:85]
	v_add_u32_e32 v170, 0x10000, v144
	global_load_dwordx2 v[154:155], v170, s[48:49]
	v_add_u32_e32 v171, 0x30000, v144
	global_load_dwordx2 v[156:157], v171, s[48:49]
	v_add_u32_e32 v172, 0x50000, v144
	global_load_dwordx2 v[158:159], v172, s[48:49]
	v_add_u32_e32 v173, 0x70000, v144
	global_load_dwordx2 v[160:161], v173, s[48:49]
	v_mul_f32_e32 v174, 0xbfb8aa3b, v110
	v_mul_f32_e32 v175, 0xbfb8aa3b, v111
	v_mul_f32_e32 v182, 0xbfb8aa3b, v112
	v_mul_f32_e32 v183, 0xbfb8aa3b, v113
	v_exp_f32_e32 v174, v174
	v_exp_f32_e32 v175, v175
	v_exp_f32_e32 v182, v182
	v_exp_f32_e32 v183, v183
	v_add_f32_e32 v174, 1.0, v174
	v_add_f32_e32 v175, 1.0, v175
	v_add_f32_e32 v182, 1.0, v182
	v_add_f32_e32 v183, 1.0, v183
	v_rcp_f32_e32 v202, v174
	v_rcp_f32_e32 v203, v175
	v_rcp_f32_e32 v204, v182
	v_rcp_f32_e32 v205, v183
	v_mul_f32_e32 v174, 0xbfb8aa3b, v106
	v_mul_f32_e32 v175, 0xbfb8aa3b, v107
	v_mul_f32_e32 v182, 0xbfb8aa3b, v108
	v_mul_f32_e32 v183, 0xbfb8aa3b, v109
	v_exp_f32_e32 v174, v174
	v_exp_f32_e32 v175, v175
	v_exp_f32_e32 v182, v182
	v_exp_f32_e32 v183, v183
	v_add_f32_e32 v174, 1.0, v174
	v_add_f32_e32 v175, 1.0, v175
	v_add_f32_e32 v182, 1.0, v182
	v_add_f32_e32 v183, 1.0, v183
	v_rcp_f32_e32 v206, v174
	v_rcp_f32_e32 v207, v175
	v_rcp_f32_e32 v208, v182
	v_rcp_f32_e32 v209, v183
	v_mul_f32_e32 v174, 0xbfb8aa3b, v78
	v_mul_f32_e32 v175, 0xbfb8aa3b, v79
	v_mul_f32_e32 v182, 0xbfb8aa3b, v80
	v_mul_f32_e32 v183, 0xbfb8aa3b, v81
	v_exp_f32_e32 v174, v174
	v_exp_f32_e32 v175, v175
	v_exp_f32_e32 v182, v182
	v_exp_f32_e32 v183, v183
	v_add_f32_e32 v174, 1.0, v174
	v_add_f32_e32 v175, 1.0, v175
	v_add_f32_e32 v182, 1.0, v182
	v_add_f32_e32 v183, 1.0, v183
	v_rcp_f32_e32 v210, v174
	v_rcp_f32_e32 v211, v175
	v_rcp_f32_e32 v212, v182
	v_rcp_f32_e32 v213, v183
	v_mul_f32_e32 v174, 0xbfb8aa3b, v74
	v_mul_f32_e32 v175, 0xbfb8aa3b, v75
	v_mul_f32_e32 v182, 0xbfb8aa3b, v76
	v_mul_f32_e32 v183, 0xbfb8aa3b, v77
	v_exp_f32_e32 v174, v174
	v_exp_f32_e32 v175, v175
	v_exp_f32_e32 v182, v182
	v_exp_f32_e32 v183, v183
	v_add_f32_e32 v174, 1.0, v174
	v_add_f32_e32 v175, 1.0, v175
	v_add_f32_e32 v182, 1.0, v182
	v_add_f32_e32 v183, 1.0, v183
	v_rcp_f32_e32 v214, v174
	v_rcp_f32_e32 v215, v175
	v_rcp_f32_e32 v216, v182
	v_rcp_f32_e32 v217, v183
	s_waitcnt vmcnt(10)
	v_lshlrev_b32_e32 v218, 16, v162
	v_and_b32_e32 v219, 0xffff0000, v162
	v_lshlrev_b32_e32 v220, 16, v163
	v_and_b32_e32 v221, 0xffff0000, v163
	v_pk_fma_f32 v[222:223], v[202:203], v[218:219], 0 op_sel_hi:[1,1,0]
	v_pk_fma_f32 v[224:225], v[204:205], v[220:221], 0 op_sel_hi:[1,1,0]
	v_lshlrev_b32_e32 v218, 16, v164
	v_and_b32_e32 v219, 0xffff0000, v164
	v_lshlrev_b32_e32 v220, 16, v165
	v_and_b32_e32 v221, 0xffff0000, v165
	v_pk_fma_f32 v[222:223], v[206:207], v[218:219], v[222:223]
	v_pk_fma_f32 v[224:225], v[208:209], v[220:221], v[224:225]
	v_lshlrev_b32_e32 v218, 16, v166
	v_and_b32_e32 v219, 0xffff0000, v166
	v_lshlrev_b32_e32 v220, 16, v167
	v_and_b32_e32 v221, 0xffff0000, v167
	v_pk_fma_f32 v[222:223], v[210:211], v[218:219], v[222:223]
	v_pk_fma_f32 v[224:225], v[212:213], v[220:221], v[224:225]
	v_lshlrev_b32_e32 v218, 16, v168
	v_and_b32_e32 v219, 0xffff0000, v168
	v_lshlrev_b32_e32 v220, 16, v169
	v_and_b32_e32 v221, 0xffff0000, v169
	v_pk_fma_f32 v[222:223], v[214:215], v[218:219], v[222:223]
	v_pk_fma_f32 v[224:225], v[216:217], v[220:221], v[224:225]
	v_add_u32_e32 v230, 0x10000, v145
	v_cvt_pk_bf16_f32 v226, v222, v223
	v_cvt_pk_bf16_f32 v227, v224, v225
	global_store_dwordx2 v230, v[226:227], s[84:85]
	v_add_u32_e32 v170, 0x12000, v144
	global_load_dwordx2 v[162:163], v170, s[48:49]
	v_add_u32_e32 v171, 0x32000, v144
	global_load_dwordx2 v[164:165], v171, s[48:49]
	v_add_u32_e32 v172, 0x52000, v144
	global_load_dwordx2 v[166:167], v172, s[48:49]
	v_add_u32_e32 v173, 0x72000, v144
	global_load_dwordx2 v[168:169], v173, s[48:49]
	v_mul_f32_e32 v174, 0xbfb8aa3b, v102
	v_mul_f32_e32 v175, 0xbfb8aa3b, v103
	v_mul_f32_e32 v182, 0xbfb8aa3b, v104
	v_mul_f32_e32 v183, 0xbfb8aa3b, v105
	v_exp_f32_e32 v174, v174
	v_exp_f32_e32 v175, v175
	v_exp_f32_e32 v182, v182
	v_exp_f32_e32 v183, v183
	v_add_f32_e32 v174, 1.0, v174
	v_add_f32_e32 v175, 1.0, v175
	v_add_f32_e32 v182, 1.0, v182
	v_add_f32_e32 v183, 1.0, v183
	v_rcp_f32_e32 v202, v174
	v_rcp_f32_e32 v203, v175
	v_rcp_f32_e32 v204, v182
	v_rcp_f32_e32 v205, v183
	v_mul_f32_e32 v174, 0xbfb8aa3b, v98
	v_mul_f32_e32 v175, 0xbfb8aa3b, v99
	v_mul_f32_e32 v182, 0xbfb8aa3b, v100
	v_mul_f32_e32 v183, 0xbfb8aa3b, v101
	v_exp_f32_e32 v174, v174
	v_exp_f32_e32 v175, v175
	v_exp_f32_e32 v182, v182
	v_exp_f32_e32 v183, v183
	v_add_f32_e32 v174, 1.0, v174
	v_add_f32_e32 v175, 1.0, v175
	v_add_f32_e32 v182, 1.0, v182
	v_add_f32_e32 v183, 1.0, v183
	v_rcp_f32_e32 v206, v174
	v_rcp_f32_e32 v207, v175
	v_rcp_f32_e32 v208, v182
	v_rcp_f32_e32 v209, v183
	v_mul_f32_e32 v174, 0xbfb8aa3b, v70
	v_mul_f32_e32 v175, 0xbfb8aa3b, v71
	v_mul_f32_e32 v182, 0xbfb8aa3b, v72
	v_mul_f32_e32 v183, 0xbfb8aa3b, v73
	v_exp_f32_e32 v174, v174
	v_exp_f32_e32 v175, v175
	v_exp_f32_e32 v182, v182
	v_exp_f32_e32 v183, v183
	v_add_f32_e32 v174, 1.0, v174
	v_add_f32_e32 v175, 1.0, v175
	v_add_f32_e32 v182, 1.0, v182
	v_add_f32_e32 v183, 1.0, v183
	v_rcp_f32_e32 v210, v174
	v_rcp_f32_e32 v211, v175
	v_rcp_f32_e32 v212, v182
	v_rcp_f32_e32 v213, v183
	v_mul_f32_e32 v174, 0xbfb8aa3b, v66
	v_mul_f32_e32 v175, 0xbfb8aa3b, v67
	v_mul_f32_e32 v182, 0xbfb8aa3b, v68
	v_mul_f32_e32 v183, 0xbfb8aa3b, v69
	v_exp_f32_e32 v174, v174
	v_exp_f32_e32 v175, v175
	v_exp_f32_e32 v182, v182
	v_exp_f32_e32 v183, v183
	v_add_f32_e32 v174, 1.0, v174
	v_add_f32_e32 v175, 1.0, v175
	v_add_f32_e32 v182, 1.0, v182
	v_add_f32_e32 v183, 1.0, v183
	v_rcp_f32_e32 v214, v174
	v_rcp_f32_e32 v215, v175
	v_rcp_f32_e32 v216, v182
	v_rcp_f32_e32 v217, v183
	s_waitcnt vmcnt(10)
; __device__ __forceinline__ float lo2f(unsigned w) { return __uint_as_float(w << 16); }
; __device__ __forceinline__ float hi2f(unsigned w) { return __uint_as_float(w & 0xffff0000u); }
; __device__ __forceinline__ float sigm(float x) { return __builtin_amdgcn_rcpf(1.f + __expf(-x)); }
;   __device__ __forceinline__ void operator()(const f32x4 (&acc)[2][2][4][2], const Unit& u, int wr, int wc, int fr, int fq) const {
;     ...
;       const int q = s - 4, bjq = q >> 1, nq = q & 1;
; #pragma unroll
;       for (int ai = 0; ai < 2; ++ai)
; #pragma unroll
;         for (int m = 0; m < 4; ++m) {
;           float o[4] = {0.f, 0.f, 0.f, 0.f};
; #pragma unroll
;           for (int bj = 0; bj < 2; ++bj)
; #pragma unroll
;             for (int n = 0; n < 2; ++n) {
;               const int ib = 2 * bj + n;
;               const uint2 b2 = *(reinterpret_cast<const uint2*>(brs + (size_t)(ib * 16 + (ai * 2 + bjq) * 4 + m) * 512 + tid) + nq);
;               const f32x4 g = acc[ai][bj][m][n];
;               o[0] += sigm(g[0]) * lo2f(b2.x); o[1] += sigm(g[1]) * hi2f(b2.x);
;               o[2] += sigm(g[2]) * lo2f(b2.y); o[3] += sigm(g[3]) * hi2f(b2.y);
;             }
;           const int r = u.pm * 256 + ai * 128 + wr * 64 + m * 16 + fr;
;           const int d = dq * 256 + 64 * q + 16 * wc + 4 * fq;
;           uint2 w; w.x = pack2(o[0], o[1]); w.y = pack2(o[2], o[3]);
;           *reinterpret_cast<uint2*>(ACC + (size_t)r * 1024 + d) = w;
;         }
	v_lshlrev_b32_e32 v218, 16, v146
	v_and_b32_e32 v219, 0xffff0000, v146
	v_lshlrev_b32_e32 v220, 16, v147
	v_and_b32_e32 v221, 0xffff0000, v147
	v_pk_fma_f32 v[222:223], v[202:203], v[218:219], 0 op_sel_hi:[1,1,0]
	v_pk_fma_f32 v[224:225], v[204:205], v[220:221], 0 op_sel_hi:[1,1,0]
	v_lshlrev_b32_e32 v218, 16, v148
	v_and_b32_e32 v219, 0xffff0000, v148
	v_lshlrev_b32_e32 v220, 16, v149
	v_and_b32_e32 v221, 0xffff0000, v149
	v_pk_fma_f32 v[222:223], v[206:207], v[218:219], v[222:223]
	v_pk_fma_f32 v[224:225], v[208:209], v[220:221], v[224:225]
	v_lshlrev_b32_e32 v218, 16, v150
	v_and_b32_e32 v219, 0xffff0000, v150
	v_lshlrev_b32_e32 v220, 16, v151
	v_and_b32_e32 v221, 0xffff0000, v151
	v_pk_fma_f32 v[222:223], v[210:211], v[218:219], v[222:223]
	v_pk_fma_f32 v[224:225], v[212:213], v[220:221], v[224:225]
	v_lshlrev_b32_e32 v218, 16, v152
	v_and_b32_e32 v219, 0xffff0000, v152
	v_lshlrev_b32_e32 v220, 16, v153
	v_and_b32_e32 v221, 0xffff0000, v153
	v_pk_fma_f32 v[222:223], v[214:215], v[218:219], v[222:223]
	v_pk_fma_f32 v[224:225], v[216:217], v[220:221], v[224:225]
	v_add_u32_e32 v231, 0x18000, v145
	v_cvt_pk_bf16_f32 v228, v222, v223
	v_cvt_pk_bf16_f32 v229, v224, v225
	global_store_dwordx2 v231, v[228:229], s[84:85]
	v_add_u32_e32 v170, 0x14000, v144
	global_load_dwordx2 v[146:147], v170, s[48:49]
	v_add_u32_e32 v171, 0x34000, v144
	global_load_dwordx2 v[148:149], v171, s[48:49]
	v_add_u32_e32 v172, 0x54000, v144
	global_load_dwordx2 v[150:151], v172, s[48:49]
	v_add_u32_e32 v173, 0x74000, v144
	global_load_dwordx2 v[152:153], v173, s[48:49]
	v_mul_f32_e32 v174, 0xbfb8aa3b, v62
	v_mul_f32_e32 v175, 0xbfb8aa3b, v63
	v_mul_f32_e32 v182, 0xbfb8aa3b, v64
	v_mul_f32_e32 v183, 0xbfb8aa3b, v65
	v_exp_f32_e32 v174, v174
	v_exp_f32_e32 v175, v175
	v_exp_f32_e32 v182, v182
	v_exp_f32_e32 v183, v183
	v_add_f32_e32 v174, 1.0, v174
	v_add_f32_e32 v175, 1.0, v175
	v_add_f32_e32 v182, 1.0, v182
	v_add_f32_e32 v183, 1.0, v183
	v_rcp_f32_e32 v202, v174
	v_rcp_f32_e32 v203, v175
	v_rcp_f32_e32 v204, v182
	v_rcp_f32_e32 v205, v183
	v_mul_f32_e32 v174, 0xbfb8aa3b, v58
	v_mul_f32_e32 v175, 0xbfb8aa3b, v59
	v_mul_f32_e32 v182, 0xbfb8aa3b, v60
	v_mul_f32_e32 v183, 0xbfb8aa3b, v61
	v_exp_f32_e32 v174, v174
	v_exp_f32_e32 v175, v175
	v_exp_f32_e32 v182, v182
	v_exp_f32_e32 v183, v183
	v_add_f32_e32 v174, 1.0, v174
	v_add_f32_e32 v175, 1.0, v175
	v_add_f32_e32 v182, 1.0, v182
	v_add_f32_e32 v183, 1.0, v183
	v_rcp_f32_e32 v206, v174
	v_rcp_f32_e32 v207, v175
	v_rcp_f32_e32 v208, v182
	v_rcp_f32_e32 v209, v183
	v_mul_f32_e32 v174, 0xbfb8aa3b, v30
	v_mul_f32_e32 v175, 0xbfb8aa3b, v31
	v_mul_f32_e32 v182, 0xbfb8aa3b, v32
	v_mul_f32_e32 v183, 0xbfb8aa3b, v33
	v_exp_f32_e32 v174, v174
	v_exp_f32_e32 v175, v175
	v_exp_f32_e32 v182, v182
	v_exp_f32_e32 v183, v183
	v_add_f32_e32 v174, 1.0, v174
	v_add_f32_e32 v175, 1.0, v175
	v_add_f32_e32 v182, 1.0, v182
	v_add_f32_e32 v183, 1.0, v183
	v_rcp_f32_e32 v210, v174
	v_rcp_f32_e32 v211, v175
	v_rcp_f32_e32 v212, v182
	v_rcp_f32_e32 v213, v183
	v_mul_f32_e32 v174, 0xbfb8aa3b, v26
	v_mul_f32_e32 v175, 0xbfb8aa3b, v27
	v_mul_f32_e32 v182, 0xbfb8aa3b, v28
	v_mul_f32_e32 v183, 0xbfb8aa3b, v29
	v_exp_f32_e32 v174, v174
	v_exp_f32_e32 v175, v175
	v_exp_f32_e32 v182, v182
	v_exp_f32_e32 v183, v183
	v_add_f32_e32 v174, 1.0, v174
	v_add_f32_e32 v175, 1.0, v175
	v_add_f32_e32 v182, 1.0, v182
	v_add_f32_e32 v183, 1.0, v183
	v_rcp_f32_e32 v214, v174
	v_rcp_f32_e32 v215, v175
	v_rcp_f32_e32 v216, v182
	v_rcp_f32_e32 v217, v183
	s_waitcnt vmcnt(10)
	v_lshlrev_b32_e32 v218, 16, v154
	v_and_b32_e32 v219, 0xffff0000, v154
	v_lshlrev_b32_e32 v220, 16, v155
	v_and_b32_e32 v221, 0xffff0000, v155
	v_pk_fma_f32 v[222:223], v[202:203], v[218:219], 0 op_sel_hi:[1,1,0]
	v_pk_fma_f32 v[224:225], v[204:205], v[220:221], 0 op_sel_hi:[1,1,0]
	v_lshlrev_b32_e32 v218, 16, v156
	v_and_b32_e32 v219, 0xffff0000, v156
	v_lshlrev_b32_e32 v220, 16, v157
	v_and_b32_e32 v221, 0xffff0000, v157
	v_pk_fma_f32 v[222:223], v[206:207], v[218:219], v[222:223]
	v_pk_fma_f32 v[224:225], v[208:209], v[220:221], v[224:225]
	v_lshlrev_b32_e32 v218, 16, v158
	v_and_b32_e32 v219, 0xffff0000, v158
	v_lshlrev_b32_e32 v220, 16, v159
	v_and_b32_e32 v221, 0xffff0000, v159
	v_pk_fma_f32 v[222:223], v[210:211], v[218:219], v[222:223]
	v_pk_fma_f32 v[224:225], v[212:213], v[220:221], v[224:225]
	v_lshlrev_b32_e32 v218, 16, v160
	v_and_b32_e32 v219, 0xffff0000, v160
	v_lshlrev_b32_e32 v220, 16, v161
	v_and_b32_e32 v221, 0xffff0000, v161
	v_pk_fma_f32 v[222:223], v[214:215], v[218:219], v[222:223]
	v_pk_fma_f32 v[224:225], v[216:217], v[220:221], v[224:225]
	v_add_u32_e32 v230, 0x40000, v145
	v_cvt_pk_bf16_f32 v226, v222, v223
	v_cvt_pk_bf16_f32 v227, v224, v225
	global_store_dwordx2 v230, v[226:227], s[84:85]
	v_add_u32_e32 v170, 0x16000, v144
	global_load_dwordx2 v[154:155], v170, s[48:49]
	v_add_u32_e32 v171, 0x36000, v144
	global_load_dwordx2 v[156:157], v171, s[48:49]
	v_add_u32_e32 v172, 0x56000, v144
	global_load_dwordx2 v[158:159], v172, s[48:49]
	v_add_u32_e32 v173, 0x76000, v144
	global_load_dwordx2 v[160:161], v173, s[48:49]
	v_mul_f32_e32 v174, 0xbfb8aa3b, v54
	v_mul_f32_e32 v175, 0xbfb8aa3b, v55
	v_mul_f32_e32 v182, 0xbfb8aa3b, v56
	v_mul_f32_e32 v183, 0xbfb8aa3b, v57
	v_exp_f32_e32 v174, v174
	v_exp_f32_e32 v175, v175
	v_exp_f32_e32 v182, v182
	v_exp_f32_e32 v183, v183
	v_add_f32_e32 v174, 1.0, v174
	v_add_f32_e32 v175, 1.0, v175
	v_add_f32_e32 v182, 1.0, v182
	v_add_f32_e32 v183, 1.0, v183
	v_rcp_f32_e32 v202, v174
	v_rcp_f32_e32 v203, v175
	v_rcp_f32_e32 v204, v182
	v_rcp_f32_e32 v205, v183
	v_mul_f32_e32 v174, 0xbfb8aa3b, v50
	v_mul_f32_e32 v175, 0xbfb8aa3b, v51
	v_mul_f32_e32 v182, 0xbfb8aa3b, v52
	v_mul_f32_e32 v183, 0xbfb8aa3b, v53
	v_exp_f32_e32 v174, v174
	v_exp_f32_e32 v175, v175
	v_exp_f32_e32 v182, v182
	v_exp_f32_e32 v183, v183
	v_add_f32_e32 v174, 1.0, v174
	v_add_f32_e32 v175, 1.0, v175
	v_add_f32_e32 v182, 1.0, v182
	v_add_f32_e32 v183, 1.0, v183
	v_rcp_f32_e32 v206, v174
	v_rcp_f32_e32 v207, v175
	v_rcp_f32_e32 v208, v182
	v_rcp_f32_e32 v209, v183
	v_mul_f32_e32 v174, 0xbfb8aa3b, v22
	v_mul_f32_e32 v175, 0xbfb8aa3b, v23
	v_mul_f32_e32 v182, 0xbfb8aa3b, v24
	v_mul_f32_e32 v183, 0xbfb8aa3b, v25
	v_exp_f32_e32 v174, v174
	v_exp_f32_e32 v175, v175
	v_exp_f32_e32 v182, v182
	v_exp_f32_e32 v183, v183
	v_add_f32_e32 v174, 1.0, v174
	v_add_f32_e32 v175, 1.0, v175
	v_add_f32_e32 v182, 1.0, v182
	v_add_f32_e32 v183, 1.0, v183
	v_rcp_f32_e32 v210, v174
	v_rcp_f32_e32 v211, v175
	v_rcp_f32_e32 v212, v182
	v_rcp_f32_e32 v213, v183
	v_mul_f32_e32 v174, 0xbfb8aa3b, v18
	v_mul_f32_e32 v175, 0xbfb8aa3b, v19
	v_mul_f32_e32 v182, 0xbfb8aa3b, v20
	v_mul_f32_e32 v183, 0xbfb8aa3b, v21
	v_exp_f32_e32 v174, v174
	v_exp_f32_e32 v175, v175
	v_exp_f32_e32 v182, v182
	v_exp_f32_e32 v183, v183
	v_add_f32_e32 v174, 1.0, v174
	v_add_f32_e32 v175, 1.0, v175
	v_add_f32_e32 v182, 1.0, v182
	v_add_f32_e32 v183, 1.0, v183
	v_rcp_f32_e32 v214, v174
	v_rcp_f32_e32 v215, v175
	v_rcp_f32_e32 v216, v182
	v_rcp_f32_e32 v217, v183
	s_waitcnt vmcnt(10)
; __device__ __forceinline__ float lo2f(unsigned w) { return __uint_as_float(w << 16); }
; __device__ __forceinline__ float hi2f(unsigned w) { return __uint_as_float(w & 0xffff0000u); }
; __device__ __forceinline__ float sigm(float x) { return __builtin_amdgcn_rcpf(1.f + __expf(-x)); }
;   __device__ __forceinline__ void operator()(const f32x4 (&acc)[2][2][4][2], const Unit& u, int wr, int wc, int fr, int fq) const {
;     ...
;       const int q = s - 4, bjq = q >> 1, nq = q & 1;
; #pragma unroll
;       for (int ai = 0; ai < 2; ++ai)
; #pragma unroll
;         for (int m = 0; m < 4; ++m) {
;           float o[4] = {0.f, 0.f, 0.f, 0.f};
; #pragma unroll
;           for (int bj = 0; bj < 2; ++bj)
; #pragma unroll
;             for (int n = 0; n < 2; ++n) {
;               const int ib = 2 * bj + n;
;               const uint2 b2 = *(reinterpret_cast<const uint2*>(brs + (size_t)(ib * 16 + (ai * 2 + bjq) * 4 + m) * 512 + tid) + nq);
;               const f32x4 g = acc[ai][bj][m][n];
;               o[0] += sigm(g[0]) * lo2f(b2.x); o[1] += sigm(g[1]) * hi2f(b2.x);
;               o[2] += sigm(g[2]) * lo2f(b2.y); o[3] += sigm(g[3]) * hi2f(b2.y);
;             }
;           const int r = u.pm * 256 + ai * 128 + wr * 64 + m * 16 + fr;
;           const int d = dq * 256 + 64 * q + 16 * wc + 4 * fq;
;           uint2 w; w.x = pack2(o[0], o[1]); w.y = pack2(o[2], o[3]);
;           *reinterpret_cast<uint2*>(ACC + (size_t)r * 1024 + d) = w;
;         }
	v_lshlrev_b32_e32 v218, 16, v162
	v_and_b32_e32 v219, 0xffff0000, v162
	v_lshlrev_b32_e32 v220, 16, v163
	v_and_b32_e32 v221, 0xffff0000, v163
	v_pk_fma_f32 v[222:223], v[202:203], v[218:219], 0 op_sel_hi:[1,1,0]
	v_pk_fma_f32 v[224:225], v[204:205], v[220:221], 0 op_sel_hi:[1,1,0]
	v_lshlrev_b32_e32 v218, 16, v164
	v_and_b32_e32 v219, 0xffff0000, v164
	v_lshlrev_b32_e32 v220, 16, v165
	v_and_b32_e32 v221, 0xffff0000, v165
	v_pk_fma_f32 v[222:223], v[206:207], v[218:219], v[222:223]
	v_pk_fma_f32 v[224:225], v[208:209], v[220:221], v[224:225]
	v_lshlrev_b32_e32 v218, 16, v166
	v_and_b32_e32 v219, 0xffff0000, v166
	v_lshlrev_b32_e32 v220, 16, v167
	v_and_b32_e32 v221, 0xffff0000, v167
	v_pk_fma_f32 v[222:223], v[210:211], v[218:219], v[222:223]
	v_pk_fma_f32 v[224:225], v[212:213], v[220:221], v[224:225]
	v_lshlrev_b32_e32 v218, 16, v168
	v_and_b32_e32 v219, 0xffff0000, v168
	v_lshlrev_b32_e32 v220, 16, v169
	v_and_b32_e32 v221, 0xffff0000, v169
	v_pk_fma_f32 v[222:223], v[214:215], v[218:219], v[222:223]
	v_pk_fma_f32 v[224:225], v[216:217], v[220:221], v[224:225]
	v_add_u32_e32 v231, 0x48000, v145
	v_cvt_pk_bf16_f32 v228, v222, v223
	v_cvt_pk_bf16_f32 v229, v224, v225
	global_store_dwordx2 v231, v[228:229], s[84:85]
	v_mul_f32_e32 v174, 0xbfb8aa3b, v46
	v_mul_f32_e32 v175, 0xbfb8aa3b, v47
	v_mul_f32_e32 v182, 0xbfb8aa3b, v48
	v_mul_f32_e32 v183, 0xbfb8aa3b, v49
	v_exp_f32_e32 v174, v174
	v_exp_f32_e32 v175, v175
	v_exp_f32_e32 v182, v182
	v_exp_f32_e32 v183, v183
	v_add_f32_e32 v174, 1.0, v174
	v_add_f32_e32 v175, 1.0, v175
	v_add_f32_e32 v182, 1.0, v182
	v_add_f32_e32 v183, 1.0, v183
	v_rcp_f32_e32 v202, v174
	v_rcp_f32_e32 v203, v175
	v_rcp_f32_e32 v204, v182
	v_rcp_f32_e32 v205, v183
	v_mul_f32_e32 v174, 0xbfb8aa3b, v42
	v_mul_f32_e32 v175, 0xbfb8aa3b, v43
	v_mul_f32_e32 v182, 0xbfb8aa3b, v44
	v_mul_f32_e32 v183, 0xbfb8aa3b, v45
	v_exp_f32_e32 v174, v174
	v_exp_f32_e32 v175, v175
	v_exp_f32_e32 v182, v182
	v_exp_f32_e32 v183, v183
	v_add_f32_e32 v174, 1.0, v174
	v_add_f32_e32 v175, 1.0, v175
	v_add_f32_e32 v182, 1.0, v182
	v_add_f32_e32 v183, 1.0, v183
	v_rcp_f32_e32 v206, v174
	v_rcp_f32_e32 v207, v175
	v_rcp_f32_e32 v208, v182
	v_rcp_f32_e32 v209, v183
	v_mul_f32_e32 v174, 0xbfb8aa3b, v14
	v_mul_f32_e32 v175, 0xbfb8aa3b, v15
	v_mul_f32_e32 v182, 0xbfb8aa3b, v16
	v_mul_f32_e32 v183, 0xbfb8aa3b, v17
	v_exp_f32_e32 v174, v174
	v_exp_f32_e32 v175, v175
	v_exp_f32_e32 v182, v182
	v_exp_f32_e32 v183, v183
	v_add_f32_e32 v174, 1.0, v174
	v_add_f32_e32 v175, 1.0, v175
	v_add_f32_e32 v182, 1.0, v182
	v_add_f32_e32 v183, 1.0, v183
	v_rcp_f32_e32 v210, v174
	v_rcp_f32_e32 v211, v175
	v_rcp_f32_e32 v212, v182
	v_rcp_f32_e32 v213, v183
	v_mul_f32_e32 v174, 0xbfb8aa3b, v10
	v_mul_f32_e32 v175, 0xbfb8aa3b, v11
	v_mul_f32_e32 v182, 0xbfb8aa3b, v12
	v_mul_f32_e32 v183, 0xbfb8aa3b, v13
	v_exp_f32_e32 v174, v174
	v_exp_f32_e32 v175, v175
	v_exp_f32_e32 v182, v182
	v_exp_f32_e32 v183, v183
	v_add_f32_e32 v174, 1.0, v174
	v_add_f32_e32 v175, 1.0, v175
	v_add_f32_e32 v182, 1.0, v182
	v_add_f32_e32 v183, 1.0, v183
	v_rcp_f32_e32 v214, v174
	v_rcp_f32_e32 v215, v175
	v_rcp_f32_e32 v216, v182
	v_rcp_f32_e32 v217, v183
	s_waitcnt vmcnt(6)
; __device__ __forceinline__ float lo2f(unsigned w) { return __uint_as_float(w << 16); }
; __device__ __forceinline__ float hi2f(unsigned w) { return __uint_as_float(w & 0xffff0000u); }
; __device__ __forceinline__ float sigm(float x) { return __builtin_amdgcn_rcpf(1.f + __expf(-x)); }
;   __device__ __forceinline__ void operator()(const f32x4 (&acc)[2][2][4][2], const Unit& u, int wr, int wc, int fr, int fq) const {
;     ...
;       const int q = s - 4, bjq = q >> 1, nq = q & 1;
; #pragma unroll
;       for (int ai = 0; ai < 2; ++ai)
; #pragma unroll
;         for (int m = 0; m < 4; ++m) {
;           float o[4] = {0.f, 0.f, 0.f, 0.f};
; #pragma unroll
;           for (int bj = 0; bj < 2; ++bj)
; #pragma unroll
;             for (int n = 0; n < 2; ++n) {
;               const int ib = 2 * bj + n;
;               const uint2 b2 = *(reinterpret_cast<const uint2*>(brs + (size_t)(ib * 16 + (ai * 2 + bjq) * 4 + m) * 512 + tid) + nq);
;               const f32x4 g = acc[ai][bj][m][n];
;               o[0] += sigm(g[0]) * lo2f(b2.x); o[1] += sigm(g[1]) * hi2f(b2.x);
;               o[2] += sigm(g[2]) * lo2f(b2.y); o[3] += sigm(g[3]) * hi2f(b2.y);
;             }
;           const int r = u.pm * 256 + ai * 128 + wr * 64 + m * 16 + fr;
;           const int d = dq * 256 + 64 * q + 16 * wc + 4 * fq;
;           uint2 w; w.x = pack2(o[0], o[1]); w.y = pack2(o[2], o[3]);
;           *reinterpret_cast<uint2*>(ACC + (size_t)r * 1024 + d) = w;
;         }
	v_lshlrev_b32_e32 v218, 16, v146
	v_and_b32_e32 v219, 0xffff0000, v146
	v_lshlrev_b32_e32 v220, 16, v147
	v_and_b32_e32 v221, 0xffff0000, v147
	v_pk_fma_f32 v[222:223], v[202:203], v[218:219], 0 op_sel_hi:[1,1,0]
	v_pk_fma_f32 v[224:225], v[204:205], v[220:221], 0 op_sel_hi:[1,1,0]
	v_lshlrev_b32_e32 v218, 16, v148
	v_and_b32_e32 v219, 0xffff0000, v148
	v_lshlrev_b32_e32 v220, 16, v149
	v_and_b32_e32 v221, 0xffff0000, v149
	v_pk_fma_f32 v[222:223], v[206:207], v[218:219], v[222:223]
	v_pk_fma_f32 v[224:225], v[208:209], v[220:221], v[224:225]
	v_lshlrev_b32_e32 v218, 16, v150
	v_and_b32_e32 v219, 0xffff0000, v150
	v_lshlrev_b32_e32 v220, 16, v151
	v_and_b32_e32 v221, 0xffff0000, v151
	v_pk_fma_f32 v[222:223], v[210:211], v[218:219], v[222:223]
	v_pk_fma_f32 v[224:225], v[212:213], v[220:221], v[224:225]
	v_lshlrev_b32_e32 v218, 16, v152
	v_and_b32_e32 v219, 0xffff0000, v152
	v_lshlrev_b32_e32 v220, 16, v153
	v_and_b32_e32 v221, 0xffff0000, v153
	v_pk_fma_f32 v[222:223], v[214:215], v[218:219], v[222:223]
	v_pk_fma_f32 v[224:225], v[216:217], v[220:221], v[224:225]
	v_add_u32_e32 v230, 0x50000, v145
	v_cvt_pk_bf16_f32 v226, v222, v223
	v_cvt_pk_bf16_f32 v227, v224, v225
	global_store_dwordx2 v230, v[226:227], s[84:85]
	v_mul_f32_e32 v174, 0xbfb8aa3b, v38
	v_mul_f32_e32 v175, 0xbfb8aa3b, v39
	v_mul_f32_e32 v182, 0xbfb8aa3b, v40
	v_mul_f32_e32 v183, 0xbfb8aa3b, v41
	v_exp_f32_e32 v174, v174
	v_exp_f32_e32 v175, v175
	v_exp_f32_e32 v182, v182
	v_exp_f32_e32 v183, v183
	v_add_f32_e32 v174, 1.0, v174
	v_add_f32_e32 v175, 1.0, v175
	v_add_f32_e32 v182, 1.0, v182
	v_add_f32_e32 v183, 1.0, v183
	v_rcp_f32_e32 v202, v174
	v_rcp_f32_e32 v203, v175
	v_rcp_f32_e32 v204, v182
	v_rcp_f32_e32 v205, v183
	v_mul_f32_e32 v174, 0xbfb8aa3b, v34
	v_mul_f32_e32 v175, 0xbfb8aa3b, v35
	v_mul_f32_e32 v182, 0xbfb8aa3b, v36
	v_mul_f32_e32 v183, 0xbfb8aa3b, v37
	v_exp_f32_e32 v174, v174
	v_exp_f32_e32 v175, v175
	v_exp_f32_e32 v182, v182
	v_exp_f32_e32 v183, v183
	v_add_f32_e32 v174, 1.0, v174
	v_add_f32_e32 v175, 1.0, v175
	v_add_f32_e32 v182, 1.0, v182
	v_add_f32_e32 v183, 1.0, v183
	v_rcp_f32_e32 v206, v174
	v_rcp_f32_e32 v207, v175
	v_rcp_f32_e32 v208, v182
	v_rcp_f32_e32 v209, v183
	v_mul_f32_e32 v174, 0xbfb8aa3b, v6
	v_mul_f32_e32 v175, 0xbfb8aa3b, v7
	v_mul_f32_e32 v182, 0xbfb8aa3b, v8
	v_mul_f32_e32 v183, 0xbfb8aa3b, v9
	v_exp_f32_e32 v174, v174
	v_exp_f32_e32 v175, v175
	v_exp_f32_e32 v182, v182
	v_exp_f32_e32 v183, v183
	v_add_f32_e32 v174, 1.0, v174
	v_add_f32_e32 v175, 1.0, v175
	v_add_f32_e32 v182, 1.0, v182
	v_add_f32_e32 v183, 1.0, v183
	v_rcp_f32_e32 v210, v174
	v_rcp_f32_e32 v211, v175
	v_rcp_f32_e32 v212, v182
	v_rcp_f32_e32 v213, v183
	v_mul_f32_e32 v174, 0xbfb8aa3b, v2
	v_mul_f32_e32 v175, 0xbfb8aa3b, v3
	v_mul_f32_e32 v182, 0xbfb8aa3b, v4
	v_mul_f32_e32 v183, 0xbfb8aa3b, v5
	v_exp_f32_e32 v174, v174
	v_exp_f32_e32 v175, v175
	v_exp_f32_e32 v182, v182
	v_exp_f32_e32 v183, v183
	v_add_f32_e32 v174, 1.0, v174
	v_add_f32_e32 v175, 1.0, v175
	v_add_f32_e32 v182, 1.0, v182
	v_add_f32_e32 v183, 1.0, v183
	v_rcp_f32_e32 v214, v174
	v_rcp_f32_e32 v215, v175
	v_rcp_f32_e32 v216, v182
	v_rcp_f32_e32 v217, v183
	s_waitcnt vmcnt(2)
	v_lshlrev_b32_e32 v218, 16, v154
	v_and_b32_e32 v219, 0xffff0000, v154
	v_lshlrev_b32_e32 v220, 16, v155
	v_and_b32_e32 v221, 0xffff0000, v155
	v_pk_fma_f32 v[222:223], v[202:203], v[218:219], 0 op_sel_hi:[1,1,0]
	v_pk_fma_f32 v[224:225], v[204:205], v[220:221], 0 op_sel_hi:[1,1,0]
	v_lshlrev_b32_e32 v218, 16, v156
	v_and_b32_e32 v219, 0xffff0000, v156
	v_lshlrev_b32_e32 v220, 16, v157
	v_and_b32_e32 v221, 0xffff0000, v157
	v_pk_fma_f32 v[222:223], v[206:207], v[218:219], v[222:223]
	v_pk_fma_f32 v[224:225], v[208:209], v[220:221], v[224:225]
	v_lshlrev_b32_e32 v218, 16, v158
	v_and_b32_e32 v219, 0xffff0000, v158
	v_lshlrev_b32_e32 v220, 16, v159
	v_and_b32_e32 v221, 0xffff0000, v159
	v_pk_fma_f32 v[222:223], v[210:211], v[218:219], v[222:223]
	v_pk_fma_f32 v[224:225], v[212:213], v[220:221], v[224:225]
	v_lshlrev_b32_e32 v218, 16, v160
	v_and_b32_e32 v219, 0xffff0000, v160
	v_lshlrev_b32_e32 v220, 16, v161
	v_and_b32_e32 v221, 0xffff0000, v161
	v_pk_fma_f32 v[222:223], v[214:215], v[218:219], v[222:223]
	v_pk_fma_f32 v[224:225], v[216:217], v[220:221], v[224:225]
	v_add_u32_e32 v231, 0x58000, v145
	v_cvt_pk_bf16_f32 v228, v222, v223
	v_cvt_pk_bf16_f32 v229, v224, v225
	global_store_dwordx2 v231, v[228:229], s[84:85]
	s_cbranch_execnz .LBB0_1415
